# scaled-state scan, consumer prefetches operands 2 tokens ahead (3 register sets), permlane prefix in producer
# speedup vs baseline: 1.0140x; 1.0021x over previous
; #define LAS __attribute__((address_space(3)))
; template <int CTRL> __device__ __forceinline__ float dpp_f(float x) { return __int_as_float(__builtin_amdgcn_update_dpp(0, __float_as_int(x), CTRL, 0xf, 0xf, false)); }
; __device__ __forceinline__ void p8_scan(const Args& a, LAS unsigned char* lds) {
;     ...
;             for (int c = 0; c < T / TC; ++c) {
;                 const int cur = c & 1;
;                 const LAS float* bt = buf + cur * TC * SPITCH;
;                 LAS float* yd = holds_y ? (ybuf + cur * TC * 64 + 4 * (4 * w + (lane >> 4)) + ((lane & 15) >> 2)) : (dump + lane);
;                 ScanOps o; scan_ld(o, bt, jq4, myrow);
; #pragma unroll 16
;                 for (int tt = 0; tt < TC; ++tt) {
;                     ScanOps n; scan_ld(n, bt + (tt + 1 < TC ? tt + 1 : tt) * SPITCH, jq4, myrow);
;                     __builtin_amdgcn_sched_barrier(0);
;                     f32x2 ta = S01 * o.al.lo, ty = S01 * o.wr.lo; ta = S23 * o.al.hi + ta; ty = S23 * o.wr.hi + ty;
;                     float pa = ta.x + ta.y, py = ty.x + ty.y;
;                     f32x2 kv01 = o.kv.lo * o.vi, kv23 = o.kv.hi * o.vi;
;     ...
;                     asm volatile("" : "+v"(kv01), "+v"(kv23), "+v"(vc));
;                     pa += dpp_f<0x121>(pa); py += dpp_f<0x121>(py); pa += dpp_f<0x122>(pa); py += dpp_f<0x122>(py);
;                     pa += dpp_f<0x124>(pa); pa += dpp_f<0x128>(pa);
;                     S01 = S01 * o.wv.lo + (o.be.lo * pa + kv01);
;                     S23 = S23 * o.wv.hi + (o.be.hi * pa + kv23);
;     ...
;                     __builtin_amdgcn_sched_barrier(0);
;                     o = n;
;                 }
.LBB0_1090:
	s_and_b32 s43, s14, 1
	s_mul_i32 s52, s43, 0xc400
	s_lshl_b32 s43, s43, 13
	v_lshl_add_u32 v38, v27, 2, s52
	v_lshl_add_u32 v39, v1, 2, s52
	v_add_u32_e32 v41, s43, v123
	v_cndmask_b32_e64 v41, v124, v41, s[2:3]
	ds_read_b128 v[10:13], v38 offset:512
	ds_read_b128 v[6:9], v38 offset:256
	ds_read_b32 v28, v39 offset:1280
	ds_read_b128 v[14:17], v38 offset:768
	ds_read_b128 v[18:21], v38 offset:1024
	ds_read_b128 v[50:53], v38 offset:2080
	ds_read_b128 v[46:49], v38 offset:1824
	ds_read_b32 v62, v39 offset:2848
	ds_read_b128 v[54:57], v38 offset:2336
	ds_read_b128 v[58:61], v38 offset:2592
	s_waitcnt lgkmcnt(6)
	v_pk_mul_f32 v[34:35], v[22:23], v[10:11]
	v_pk_fma_f32 v[34:35], v[24:25], v[12:13], v[34:35]
	ds_read_b128 v[178:181], v38 offset:3648
	ds_read_b128 v[174:177], v38 offset:3392
	ds_read_b32 v190, v39 offset:4416
	ds_read_b128 v[182:185], v38 offset:3904
	ds_read_b128 v[186:189], v38 offset:4160
	v_add_f32_e32 v34, v34, v35
	v_pk_fma_f32 v[22:23], v[6:7], v[28:29], v[22:23] op_sel_hi:[1,0,1]
	v_pk_fma_f32 v[24:25], v[8:9], v[28:29], v[24:25] op_sel_hi:[1,0,1]
	v_add_f32_dpp v34, v34, v34 row_ror:1 row_mask:0xf bank_mask:0xf bound_ctrl:1
	s_nop 0
	s_nop 0
	v_add_f32_dpp v34, v34, v34 row_ror:2 row_mask:0xf bank_mask:0xf bound_ctrl:1
	s_nop 0
	s_nop 0
	v_add_f32_dpp v34, v34, v34 row_ror:4 row_mask:0xf bank_mask:0xf bound_ctrl:1
	s_nop 0
	s_nop 0
	v_add_f32_dpp v34, v34, v34 row_ror:8 row_mask:0xf bank_mask:0xf bound_ctrl:1
	v_pk_fma_f32 v[22:23], v[14:15], v[34:35], v[22:23] op_sel_hi:[1,0,1]
	v_pk_fma_f32 v[24:25], v[16:17], v[34:35], v[24:25] op_sel_hi:[1,0,1]
	s_waitcnt lgkmcnt(6)
	v_pk_mul_f32 v[34:35], v[22:23], v[50:51]
	v_pk_mul_f32 v[36:37], v[22:23], v[18:19]
	v_pk_fma_f32 v[34:35], v[24:25], v[52:53], v[34:35]
	v_pk_fma_f32 v[36:37], v[24:25], v[20:21], v[36:37]
	ds_read_b128 v[10:13], v38 offset:5216
	ds_read_b128 v[6:9], v38 offset:4960
	ds_read_b32 v28, v39 offset:5984
	ds_read_b128 v[14:17], v38 offset:5472
	ds_read_b128 v[18:21], v38 offset:5728
	v_add_f32_e32 v34, v34, v35
	v_add_f32_e32 v36, v36, v37
	v_pk_fma_f32 v[22:23], v[46:47], v[62:63], v[22:23] op_sel_hi:[1,0,1]
	v_add_f32_dpp v34, v34, v34 row_ror:1 row_mask:0xf bank_mask:0xf bound_ctrl:1
	v_add_f32_dpp v36, v36, v36 row_ror:1 row_mask:0xf bank_mask:0xf bound_ctrl:1
	v_pk_fma_f32 v[24:25], v[48:49], v[62:63], v[24:25] op_sel_hi:[1,0,1]
	v_add_f32_dpp v34, v34, v34 row_ror:2 row_mask:0xf bank_mask:0xf bound_ctrl:1
	v_add_f32_dpp v36, v36, v36 row_ror:2 row_mask:0xf bank_mask:0xf bound_ctrl:1
	s_nop 0
	v_add_f32_dpp v34, v34, v34 row_ror:4 row_mask:0xf bank_mask:0xf bound_ctrl:1
	s_nop 0
	s_nop 0
	v_add_f32_dpp v34, v34, v34 row_ror:8 row_mask:0xf bank_mask:0xf bound_ctrl:1
	v_pk_fma_f32 v[22:23], v[54:55], v[34:35], v[22:23] op_sel_hi:[1,0,1]
	v_pk_fma_f32 v[24:25], v[56:57], v[34:35], v[24:25] op_sel_hi:[1,0,1]
	s_waitcnt lgkmcnt(6)
	v_pk_mul_f32 v[34:35], v[22:23], v[178:179]
	v_pk_mul_f32 v[66:67], v[22:23], v[58:59]
	v_pk_fma_f32 v[34:35], v[24:25], v[180:181], v[34:35]
	v_pk_fma_f32 v[66:67], v[24:25], v[60:61], v[66:67]
	ds_read_b128 v[50:53], v38 offset:6784
	ds_read_b128 v[46:49], v38 offset:6528
	ds_read_b32 v62, v39 offset:7552
	ds_read_b128 v[54:57], v38 offset:7040
	ds_read_b128 v[58:61], v38 offset:7296
	v_add_f32_e32 v34, v34, v35
	v_add_f32_e32 v66, v66, v67
	v_pk_fma_f32 v[22:23], v[174:175], v[190:191], v[22:23] op_sel_hi:[1,0,1]
	v_add_f32_dpp v34, v34, v34 row_ror:1 row_mask:0xf bank_mask:0xf bound_ctrl:1
	v_add_f32_dpp v66, v66, v66 row_ror:1 row_mask:0xf bank_mask:0xf bound_ctrl:1
	v_pk_fma_f32 v[24:25], v[176:177], v[190:191], v[24:25] op_sel_hi:[1,0,1]
	v_add_f32_dpp v34, v34, v34 row_ror:2 row_mask:0xf bank_mask:0xf bound_ctrl:1
	v_add_f32_dpp v66, v66, v66 row_ror:2 row_mask:0xf bank_mask:0xf bound_ctrl:1
	ds_write2st64_b32 v41, v36, v66 offset0:0 offset1:1
	v_add_f32_dpp v34, v34, v34 row_ror:4 row_mask:0xf bank_mask:0xf bound_ctrl:1
	s_nop 0
	s_nop 0
	v_add_f32_dpp v34, v34, v34 row_ror:8 row_mask:0xf bank_mask:0xf bound_ctrl:1
	v_pk_fma_f32 v[22:23], v[182:183], v[34:35], v[22:23] op_sel_hi:[1,0,1]
	v_pk_fma_f32 v[24:25], v[184:185], v[34:35], v[24:25] op_sel_hi:[1,0,1]
	s_waitcnt lgkmcnt(7)
	v_pk_mul_f32 v[34:35], v[22:23], v[10:11]
	v_pk_mul_f32 v[36:37], v[22:23], v[186:187]
	v_pk_fma_f32 v[34:35], v[24:25], v[12:13], v[34:35]
	v_pk_fma_f32 v[36:37], v[24:25], v[188:189], v[36:37]
	ds_read_b128 v[178:181], v38 offset:8352
	ds_read_b128 v[174:177], v38 offset:8096
	ds_read_b32 v190, v39 offset:9120
	ds_read_b128 v[182:185], v38 offset:8608
	ds_read_b128 v[186:189], v38 offset:8864
	v_add_f32_e32 v34, v34, v35
	v_add_f32_e32 v36, v36, v37
	v_pk_fma_f32 v[22:23], v[6:7], v[28:29], v[22:23] op_sel_hi:[1,0,1]
	v_add_f32_dpp v34, v34, v34 row_ror:1 row_mask:0xf bank_mask:0xf bound_ctrl:1
	v_add_f32_dpp v36, v36, v36 row_ror:1 row_mask:0xf bank_mask:0xf bound_ctrl:1
	v_pk_fma_f32 v[24:25], v[8:9], v[28:29], v[24:25] op_sel_hi:[1,0,1]
	v_add_f32_dpp v34, v34, v34 row_ror:2 row_mask:0xf bank_mask:0xf bound_ctrl:1
	v_add_f32_dpp v36, v36, v36 row_ror:2 row_mask:0xf bank_mask:0xf bound_ctrl:1
	s_nop 0
	v_add_f32_dpp v34, v34, v34 row_ror:4 row_mask:0xf bank_mask:0xf bound_ctrl:1
	s_nop 0
	s_nop 0
	v_add_f32_dpp v34, v34, v34 row_ror:8 row_mask:0xf bank_mask:0xf bound_ctrl:1
	v_pk_fma_f32 v[22:23], v[14:15], v[34:35], v[22:23] op_sel_hi:[1,0,1]
	v_pk_fma_f32 v[24:25], v[16:17], v[34:35], v[24:25] op_sel_hi:[1,0,1]
	s_waitcnt lgkmcnt(7)
; template <int CTRL> __device__ __forceinline__ float dpp_f(float x) { return __int_as_float(__builtin_amdgcn_update_dpp(0, __float_as_int(x), CTRL, 0xf, 0xf, false)); }
; __device__ __forceinline__ void p8_scan(const Args& a, LAS unsigned char* lds) {
;     ...
; #pragma unroll 16
;                 for (int tt = 0; tt < TC; ++tt) {
;                     ScanOps n; scan_ld(n, bt + (tt + 1 < TC ? tt + 1 : tt) * SPITCH, jq4, myrow);
;                     __builtin_amdgcn_sched_barrier(0);
;                     f32x2 ta = S01 * o.al.lo, ty = S01 * o.wr.lo; ta = S23 * o.al.hi + ta; ty = S23 * o.wr.hi + ty;
;                     float pa = ta.x + ta.y, py = ty.x + ty.y;
;                     f32x2 kv01 = o.kv.lo * o.vi, kv23 = o.kv.hi * o.vi;
;     ...
;                     asm volatile("" : "+v"(kv01), "+v"(kv23), "+v"(vc));
;                     pa += dpp_f<0x121>(pa); py += dpp_f<0x121>(py); pa += dpp_f<0x122>(pa); py += dpp_f<0x122>(py);
;                     pa += dpp_f<0x124>(pa); pa += dpp_f<0x128>(pa);
;                     S01 = S01 * o.wv.lo + (o.be.lo * pa + kv01);
;                     S23 = S23 * o.wv.hi + (o.be.hi * pa + kv23);
;     ...
;                     __builtin_amdgcn_sched_barrier(0);
;                     o = n;
;                 }
	v_pk_mul_f32 v[34:35], v[22:23], v[50:51]
	v_pk_mul_f32 v[66:67], v[22:23], v[18:19]
	v_pk_fma_f32 v[34:35], v[24:25], v[52:53], v[34:35]
	v_pk_fma_f32 v[66:67], v[24:25], v[20:21], v[66:67]
	ds_read_b128 v[10:13], v38 offset:9920
	ds_read_b128 v[6:9], v38 offset:9664
	ds_read_b32 v28, v39 offset:10688
	ds_read_b128 v[14:17], v38 offset:10176
	ds_read_b128 v[18:21], v38 offset:10432
	v_add_f32_e32 v34, v34, v35
	v_add_f32_e32 v66, v66, v67
	v_pk_fma_f32 v[22:23], v[46:47], v[62:63], v[22:23] op_sel_hi:[1,0,1]
	v_add_f32_dpp v34, v34, v34 row_ror:1 row_mask:0xf bank_mask:0xf bound_ctrl:1
	v_add_f32_dpp v66, v66, v66 row_ror:1 row_mask:0xf bank_mask:0xf bound_ctrl:1
	v_pk_fma_f32 v[24:25], v[48:49], v[62:63], v[24:25] op_sel_hi:[1,0,1]
	v_add_f32_dpp v34, v34, v34 row_ror:2 row_mask:0xf bank_mask:0xf bound_ctrl:1
	v_add_f32_dpp v66, v66, v66 row_ror:2 row_mask:0xf bank_mask:0xf bound_ctrl:1
	ds_write2st64_b32 v41, v36, v66 offset0:2 offset1:3
	v_add_f32_dpp v34, v34, v34 row_ror:4 row_mask:0xf bank_mask:0xf bound_ctrl:1
	s_nop 0
	s_nop 0
	v_add_f32_dpp v34, v34, v34 row_ror:8 row_mask:0xf bank_mask:0xf bound_ctrl:1
	v_pk_fma_f32 v[22:23], v[54:55], v[34:35], v[22:23] op_sel_hi:[1,0,1]
	v_pk_fma_f32 v[24:25], v[56:57], v[34:35], v[24:25] op_sel_hi:[1,0,1]
	s_waitcnt lgkmcnt(7)
	v_pk_mul_f32 v[34:35], v[22:23], v[178:179]
	v_pk_mul_f32 v[36:37], v[22:23], v[58:59]
	v_pk_fma_f32 v[34:35], v[24:25], v[180:181], v[34:35]
	v_pk_fma_f32 v[36:37], v[24:25], v[60:61], v[36:37]
	ds_read_b128 v[50:53], v38 offset:11488
	ds_read_b128 v[46:49], v38 offset:11232
	ds_read_b32 v62, v39 offset:12256
	ds_read_b128 v[42:45], v38 offset:10976
	ds_read_b128 v[54:57], v38 offset:11744
	ds_read_b128 v[58:61], v38 offset:12000
	v_add_f32_e32 v34, v34, v35
	v_add_f32_e32 v36, v36, v37
	v_pk_fma_f32 v[22:23], v[174:175], v[190:191], v[22:23] op_sel_hi:[1,0,1]
	v_add_f32_dpp v34, v34, v34 row_ror:1 row_mask:0xf bank_mask:0xf bound_ctrl:1
	v_add_f32_dpp v36, v36, v36 row_ror:1 row_mask:0xf bank_mask:0xf bound_ctrl:1
	v_pk_fma_f32 v[24:25], v[176:177], v[190:191], v[24:25] op_sel_hi:[1,0,1]
	v_add_f32_dpp v34, v34, v34 row_ror:2 row_mask:0xf bank_mask:0xf bound_ctrl:1
	v_add_f32_dpp v36, v36, v36 row_ror:2 row_mask:0xf bank_mask:0xf bound_ctrl:1
	s_nop 0
	v_add_f32_dpp v34, v34, v34 row_ror:4 row_mask:0xf bank_mask:0xf bound_ctrl:1
	s_nop 0
	s_nop 0
	v_add_f32_dpp v34, v34, v34 row_ror:8 row_mask:0xf bank_mask:0xf bound_ctrl:1
	v_pk_fma_f32 v[22:23], v[182:183], v[34:35], v[22:23] op_sel_hi:[1,0,1]
	v_pk_fma_f32 v[24:25], v[184:185], v[34:35], v[24:25] op_sel_hi:[1,0,1]
	s_waitcnt lgkmcnt(8)
	v_pk_mul_f32 v[34:35], v[22:23], v[10:11]
	v_pk_mul_f32 v[66:67], v[22:23], v[186:187]
	v_pk_fma_f32 v[34:35], v[24:25], v[12:13], v[34:35]
	v_pk_fma_f32 v[66:67], v[24:25], v[188:189], v[66:67]
	ds_read_b128 v[178:181], v38 offset:13056
	ds_read_b128 v[174:177], v38 offset:12800
	ds_read_b32 v190, v39 offset:13824
	ds_read_b128 v[182:185], v38 offset:13312
	ds_read_b128 v[186:189], v38 offset:13568
	v_add_f32_e32 v34, v34, v35
	v_add_f32_e32 v66, v66, v67
	v_pk_fma_f32 v[22:23], v[6:7], v[28:29], v[22:23] op_sel_hi:[1,0,1]
	v_add_f32_dpp v34, v34, v34 row_ror:1 row_mask:0xf bank_mask:0xf bound_ctrl:1
	v_add_f32_dpp v66, v66, v66 row_ror:1 row_mask:0xf bank_mask:0xf bound_ctrl:1
	v_pk_fma_f32 v[24:25], v[8:9], v[28:29], v[24:25] op_sel_hi:[1,0,1]
	v_add_f32_dpp v34, v34, v34 row_ror:2 row_mask:0xf bank_mask:0xf bound_ctrl:1
	v_add_f32_dpp v66, v66, v66 row_ror:2 row_mask:0xf bank_mask:0xf bound_ctrl:1
	ds_write2st64_b32 v41, v36, v66 offset0:4 offset1:5
	v_add_f32_dpp v34, v34, v34 row_ror:4 row_mask:0xf bank_mask:0xf bound_ctrl:1
	s_nop 0
	s_nop 0
	v_add_f32_dpp v34, v34, v34 row_ror:8 row_mask:0xf bank_mask:0xf bound_ctrl:1
	v_pk_fma_f32 v[22:23], v[14:15], v[34:35], v[22:23] op_sel_hi:[1,0,1]
	v_pk_fma_f32 v[24:25], v[16:17], v[34:35], v[24:25] op_sel_hi:[1,0,1]
	s_waitcnt lgkmcnt(7)
	v_pk_mul_f32 v[34:35], v[22:23], v[50:51]
	v_pk_mul_f32 v[36:37], v[22:23], v[18:19]
	v_pk_fma_f32 v[34:35], v[24:25], v[52:53], v[34:35]
	v_pk_fma_f32 v[36:37], v[24:25], v[20:21], v[36:37]
	ds_read_b128 v[10:13], v38 offset:14624
	ds_read_b128 v[6:9], v38 offset:14368
	ds_read_b32 v28, v39 offset:15392
	ds_read_b128 v[14:17], v38 offset:14880
	ds_read_b128 v[18:21], v38 offset:15136
	v_add_f32_e32 v34, v34, v35
	v_add_f32_e32 v36, v36, v37
	v_pk_fma_f32 v[22:23], v[46:47], v[62:63], v[22:23] op_sel_hi:[1,0,1]
	v_add_f32_dpp v34, v34, v34 row_ror:1 row_mask:0xf bank_mask:0xf bound_ctrl:1
	v_add_f32_dpp v36, v36, v36 row_ror:1 row_mask:0xf bank_mask:0xf bound_ctrl:1
	v_pk_fma_f32 v[24:25], v[48:49], v[62:63], v[24:25] op_sel_hi:[1,0,1]
	v_add_f32_dpp v34, v34, v34 row_ror:2 row_mask:0xf bank_mask:0xf bound_ctrl:1
	v_add_f32_dpp v36, v36, v36 row_ror:2 row_mask:0xf bank_mask:0xf bound_ctrl:1
	s_nop 0
	v_add_f32_dpp v34, v34, v34 row_ror:4 row_mask:0xf bank_mask:0xf bound_ctrl:1
	s_nop 0
	s_nop 0
	v_add_f32_dpp v34, v34, v34 row_ror:8 row_mask:0xf bank_mask:0xf bound_ctrl:1
	v_pk_fma_f32 v[22:23], v[54:55], v[34:35], v[22:23] op_sel_hi:[1,0,1]
	v_pk_fma_f32 v[24:25], v[56:57], v[34:35], v[24:25] op_sel_hi:[1,0,1]
	s_waitcnt lgkmcnt(7)
; template <int CTRL> __device__ __forceinline__ float dpp_f(float x) { return __int_as_float(__builtin_amdgcn_update_dpp(0, __float_as_int(x), CTRL, 0xf, 0xf, false)); }
; __device__ __forceinline__ void p8_scan(const Args& a, LAS unsigned char* lds) {
;     ...
; #pragma unroll 16
;                 for (int tt = 0; tt < TC; ++tt) {
;                     ScanOps n; scan_ld(n, bt + (tt + 1 < TC ? tt + 1 : tt) * SPITCH, jq4, myrow);
;                     __builtin_amdgcn_sched_barrier(0);
;                     f32x2 ta = S01 * o.al.lo, ty = S01 * o.wr.lo; ta = S23 * o.al.hi + ta; ty = S23 * o.wr.hi + ty;
;                     float pa = ta.x + ta.y, py = ty.x + ty.y;
;                     f32x2 kv01 = o.kv.lo * o.vi, kv23 = o.kv.hi * o.vi;
;     ...
;                     asm volatile("" : "+v"(kv01), "+v"(kv23), "+v"(vc));
;                     pa += dpp_f<0x121>(pa); py += dpp_f<0x121>(py); pa += dpp_f<0x122>(pa); py += dpp_f<0x122>(py);
;                     pa += dpp_f<0x124>(pa); pa += dpp_f<0x128>(pa);
;                     S01 = S01 * o.wv.lo + (o.be.lo * pa + kv01);
;                     S23 = S23 * o.wv.hi + (o.be.hi * pa + kv23);
;     ...
;                     __builtin_amdgcn_sched_barrier(0);
;                     o = n;
;                 }
	v_pk_mul_f32 v[66:67], v[22:23], v[58:59]
	v_pk_fma_f32 v[66:67], v[24:25], v[60:61], v[66:67]
	v_pk_mul_f32 v[22:23], v[22:23], v[42:43]
	v_pk_mul_f32 v[24:25], v[24:25], v[44:45]
	v_pk_mul_f32 v[34:35], v[22:23], v[178:179]
	v_pk_fma_f32 v[34:35], v[24:25], v[180:181], v[34:35]
	ds_read_b128 v[50:53], v38 offset:16192
	ds_read_b128 v[46:49], v38 offset:15936
	ds_read_b32 v62, v39 offset:16960
	ds_read_b128 v[54:57], v38 offset:16448
	ds_read_b128 v[58:61], v38 offset:16704
	v_add_f32_e32 v34, v34, v35
	v_add_f32_e32 v66, v66, v67
	v_pk_fma_f32 v[22:23], v[174:175], v[190:191], v[22:23] op_sel_hi:[1,0,1]
	v_add_f32_dpp v34, v34, v34 row_ror:1 row_mask:0xf bank_mask:0xf bound_ctrl:1
	v_add_f32_dpp v66, v66, v66 row_ror:1 row_mask:0xf bank_mask:0xf bound_ctrl:1
	v_pk_fma_f32 v[24:25], v[176:177], v[190:191], v[24:25] op_sel_hi:[1,0,1]
	v_add_f32_dpp v34, v34, v34 row_ror:2 row_mask:0xf bank_mask:0xf bound_ctrl:1
	v_add_f32_dpp v66, v66, v66 row_ror:2 row_mask:0xf bank_mask:0xf bound_ctrl:1
	ds_write2st64_b32 v41, v36, v66 offset0:6 offset1:7
	v_add_f32_dpp v34, v34, v34 row_ror:4 row_mask:0xf bank_mask:0xf bound_ctrl:1
	s_nop 0
	s_nop 0
	v_add_f32_dpp v34, v34, v34 row_ror:8 row_mask:0xf bank_mask:0xf bound_ctrl:1
	v_pk_fma_f32 v[22:23], v[182:183], v[34:35], v[22:23] op_sel_hi:[1,0,1]
	v_pk_fma_f32 v[24:25], v[184:185], v[34:35], v[24:25] op_sel_hi:[1,0,1]
	s_waitcnt lgkmcnt(7)
	v_pk_mul_f32 v[34:35], v[22:23], v[10:11]
	v_pk_mul_f32 v[36:37], v[22:23], v[186:187]
	v_pk_fma_f32 v[34:35], v[24:25], v[12:13], v[34:35]
	v_pk_fma_f32 v[36:37], v[24:25], v[188:189], v[36:37]
	ds_read_b128 v[178:181], v38 offset:17760
	ds_read_b128 v[174:177], v38 offset:17504
	ds_read_b32 v190, v39 offset:18528
	ds_read_b128 v[182:185], v38 offset:18016
	ds_read_b128 v[186:189], v38 offset:18272
	v_add_f32_e32 v34, v34, v35
	v_add_f32_e32 v36, v36, v37
	v_pk_fma_f32 v[22:23], v[6:7], v[28:29], v[22:23] op_sel_hi:[1,0,1]
	v_add_f32_dpp v34, v34, v34 row_ror:1 row_mask:0xf bank_mask:0xf bound_ctrl:1
	v_add_f32_dpp v36, v36, v36 row_ror:1 row_mask:0xf bank_mask:0xf bound_ctrl:1
	v_pk_fma_f32 v[24:25], v[8:9], v[28:29], v[24:25] op_sel_hi:[1,0,1]
	v_add_f32_dpp v34, v34, v34 row_ror:2 row_mask:0xf bank_mask:0xf bound_ctrl:1
	v_add_f32_dpp v36, v36, v36 row_ror:2 row_mask:0xf bank_mask:0xf bound_ctrl:1
	s_nop 0
	v_add_f32_dpp v34, v34, v34 row_ror:4 row_mask:0xf bank_mask:0xf bound_ctrl:1
	s_nop 0
	s_nop 0
	v_add_f32_dpp v34, v34, v34 row_ror:8 row_mask:0xf bank_mask:0xf bound_ctrl:1
	v_pk_fma_f32 v[22:23], v[14:15], v[34:35], v[22:23] op_sel_hi:[1,0,1]
	v_pk_fma_f32 v[24:25], v[16:17], v[34:35], v[24:25] op_sel_hi:[1,0,1]
	s_waitcnt lgkmcnt(7)
	v_pk_mul_f32 v[34:35], v[22:23], v[50:51]
	v_pk_mul_f32 v[66:67], v[22:23], v[18:19]
	v_pk_fma_f32 v[34:35], v[24:25], v[52:53], v[34:35]
	v_pk_fma_f32 v[66:67], v[24:25], v[20:21], v[66:67]
	ds_read_b128 v[10:13], v38 offset:19328
	ds_read_b128 v[6:9], v38 offset:19072
	ds_read_b32 v28, v39 offset:20096
	ds_read_b128 v[14:17], v38 offset:19584
	ds_read_b128 v[18:21], v38 offset:19840
	v_add_f32_e32 v34, v34, v35
	v_add_f32_e32 v66, v66, v67
	v_pk_fma_f32 v[22:23], v[46:47], v[62:63], v[22:23] op_sel_hi:[1,0,1]
	v_add_f32_dpp v34, v34, v34 row_ror:1 row_mask:0xf bank_mask:0xf bound_ctrl:1
	v_add_f32_dpp v66, v66, v66 row_ror:1 row_mask:0xf bank_mask:0xf bound_ctrl:1
	v_pk_fma_f32 v[24:25], v[48:49], v[62:63], v[24:25] op_sel_hi:[1,0,1]
	v_add_f32_dpp v34, v34, v34 row_ror:2 row_mask:0xf bank_mask:0xf bound_ctrl:1
	v_add_f32_dpp v66, v66, v66 row_ror:2 row_mask:0xf bank_mask:0xf bound_ctrl:1
	ds_write2st64_b32 v41, v36, v66 offset0:8 offset1:9
	v_add_f32_dpp v34, v34, v34 row_ror:4 row_mask:0xf bank_mask:0xf bound_ctrl:1
	s_nop 0
	s_nop 0
	v_add_f32_dpp v34, v34, v34 row_ror:8 row_mask:0xf bank_mask:0xf bound_ctrl:1
	v_pk_fma_f32 v[22:23], v[54:55], v[34:35], v[22:23] op_sel_hi:[1,0,1]
	v_pk_fma_f32 v[24:25], v[56:57], v[34:35], v[24:25] op_sel_hi:[1,0,1]
	s_waitcnt lgkmcnt(7)
	v_pk_mul_f32 v[34:35], v[22:23], v[178:179]
	v_pk_mul_f32 v[36:37], v[22:23], v[58:59]
	v_pk_fma_f32 v[34:35], v[24:25], v[180:181], v[34:35]
	v_pk_fma_f32 v[36:37], v[24:25], v[60:61], v[36:37]
	ds_read_b128 v[50:53], v38 offset:20896
	ds_read_b128 v[46:49], v38 offset:20640
	ds_read_b32 v62, v39 offset:21664
	ds_read_b128 v[54:57], v38 offset:21152
	ds_read_b128 v[58:61], v38 offset:21408
	v_add_f32_e32 v34, v34, v35
	v_add_f32_e32 v36, v36, v37
	v_pk_fma_f32 v[22:23], v[174:175], v[190:191], v[22:23] op_sel_hi:[1,0,1]
	v_add_f32_dpp v34, v34, v34 row_ror:1 row_mask:0xf bank_mask:0xf bound_ctrl:1
	v_add_f32_dpp v36, v36, v36 row_ror:1 row_mask:0xf bank_mask:0xf bound_ctrl:1
	v_pk_fma_f32 v[24:25], v[176:177], v[190:191], v[24:25] op_sel_hi:[1,0,1]
	v_add_f32_dpp v34, v34, v34 row_ror:2 row_mask:0xf bank_mask:0xf bound_ctrl:1
	v_add_f32_dpp v36, v36, v36 row_ror:2 row_mask:0xf bank_mask:0xf bound_ctrl:1
	s_nop 0
	v_add_f32_dpp v34, v34, v34 row_ror:4 row_mask:0xf bank_mask:0xf bound_ctrl:1
	s_nop 0
	s_nop 0
	v_add_f32_dpp v34, v34, v34 row_ror:8 row_mask:0xf bank_mask:0xf bound_ctrl:1
	v_pk_fma_f32 v[22:23], v[182:183], v[34:35], v[22:23] op_sel_hi:[1,0,1]
	v_pk_fma_f32 v[24:25], v[184:185], v[34:35], v[24:25] op_sel_hi:[1,0,1]
	s_waitcnt lgkmcnt(7)
; template <int CTRL> __device__ __forceinline__ float dpp_f(float x) { return __int_as_float(__builtin_amdgcn_update_dpp(0, __float_as_int(x), CTRL, 0xf, 0xf, false)); }
; __device__ __forceinline__ void p8_scan(const Args& a, LAS unsigned char* lds) {
;     ...
; #pragma unroll 16
;                 for (int tt = 0; tt < TC; ++tt) {
;                     ScanOps n; scan_ld(n, bt + (tt + 1 < TC ? tt + 1 : tt) * SPITCH, jq4, myrow);
;                     __builtin_amdgcn_sched_barrier(0);
;                     f32x2 ta = S01 * o.al.lo, ty = S01 * o.wr.lo; ta = S23 * o.al.hi + ta; ty = S23 * o.wr.hi + ty;
;                     float pa = ta.x + ta.y, py = ty.x + ty.y;
;                     f32x2 kv01 = o.kv.lo * o.vi, kv23 = o.kv.hi * o.vi;
;     ...
;                     asm volatile("" : "+v"(kv01), "+v"(kv23), "+v"(vc));
;                     pa += dpp_f<0x121>(pa); py += dpp_f<0x121>(py); pa += dpp_f<0x122>(pa); py += dpp_f<0x122>(py);
;                     pa += dpp_f<0x124>(pa); pa += dpp_f<0x128>(pa);
;                     S01 = S01 * o.wv.lo + (o.be.lo * pa + kv01);
;                     S23 = S23 * o.wv.hi + (o.be.hi * pa + kv23);
;     ...
;                     __builtin_amdgcn_sched_barrier(0);
;                     o = n;
;                 }
	v_pk_mul_f32 v[34:35], v[22:23], v[10:11]
	v_pk_mul_f32 v[66:67], v[22:23], v[186:187]
	v_pk_fma_f32 v[34:35], v[24:25], v[12:13], v[34:35]
	v_pk_fma_f32 v[66:67], v[24:25], v[188:189], v[66:67]
	ds_read_b128 v[178:181], v38 offset:22464
	ds_read_b128 v[174:177], v38 offset:22208
	ds_read_b32 v190, v39 offset:23232
	ds_read_b128 v[182:185], v38 offset:22720
	ds_read_b128 v[186:189], v38 offset:22976
	v_add_f32_e32 v34, v34, v35
	v_add_f32_e32 v66, v66, v67
	v_pk_fma_f32 v[22:23], v[6:7], v[28:29], v[22:23] op_sel_hi:[1,0,1]
	v_add_f32_dpp v34, v34, v34 row_ror:1 row_mask:0xf bank_mask:0xf bound_ctrl:1
	v_add_f32_dpp v66, v66, v66 row_ror:1 row_mask:0xf bank_mask:0xf bound_ctrl:1
	v_pk_fma_f32 v[24:25], v[8:9], v[28:29], v[24:25] op_sel_hi:[1,0,1]
	v_add_f32_dpp v34, v34, v34 row_ror:2 row_mask:0xf bank_mask:0xf bound_ctrl:1
	v_add_f32_dpp v66, v66, v66 row_ror:2 row_mask:0xf bank_mask:0xf bound_ctrl:1
	ds_write2st64_b32 v41, v36, v66 offset0:10 offset1:11
	v_add_f32_dpp v34, v34, v34 row_ror:4 row_mask:0xf bank_mask:0xf bound_ctrl:1
	s_nop 0
	s_nop 0
	v_add_f32_dpp v34, v34, v34 row_ror:8 row_mask:0xf bank_mask:0xf bound_ctrl:1
	v_pk_fma_f32 v[22:23], v[14:15], v[34:35], v[22:23] op_sel_hi:[1,0,1]
	v_pk_fma_f32 v[24:25], v[16:17], v[34:35], v[24:25] op_sel_hi:[1,0,1]
	s_waitcnt lgkmcnt(7)
	v_pk_mul_f32 v[34:35], v[22:23], v[50:51]
	v_pk_mul_f32 v[36:37], v[22:23], v[18:19]
	v_pk_fma_f32 v[34:35], v[24:25], v[52:53], v[34:35]
	v_pk_fma_f32 v[36:37], v[24:25], v[20:21], v[36:37]
	ds_read_b128 v[10:13], v38 offset:24032
	ds_read_b128 v[6:9], v38 offset:23776
	ds_read_b32 v28, v39 offset:24800
	ds_read_b128 v[2:5], v38 offset:23520
	ds_read_b128 v[14:17], v38 offset:24288
	ds_read_b128 v[18:21], v38 offset:24544
	v_add_f32_e32 v34, v34, v35
	v_add_f32_e32 v36, v36, v37
	v_pk_fma_f32 v[22:23], v[46:47], v[62:63], v[22:23] op_sel_hi:[1,0,1]
	v_add_f32_dpp v34, v34, v34 row_ror:1 row_mask:0xf bank_mask:0xf bound_ctrl:1
	v_add_f32_dpp v36, v36, v36 row_ror:1 row_mask:0xf bank_mask:0xf bound_ctrl:1
	v_pk_fma_f32 v[24:25], v[48:49], v[62:63], v[24:25] op_sel_hi:[1,0,1]
	v_add_f32_dpp v34, v34, v34 row_ror:2 row_mask:0xf bank_mask:0xf bound_ctrl:1
	v_add_f32_dpp v36, v36, v36 row_ror:2 row_mask:0xf bank_mask:0xf bound_ctrl:1
	s_nop 0
	v_add_f32_dpp v34, v34, v34 row_ror:4 row_mask:0xf bank_mask:0xf bound_ctrl:1
	s_nop 0
	s_nop 0
	v_add_f32_dpp v34, v34, v34 row_ror:8 row_mask:0xf bank_mask:0xf bound_ctrl:1
	v_pk_fma_f32 v[22:23], v[54:55], v[34:35], v[22:23] op_sel_hi:[1,0,1]
	v_pk_fma_f32 v[24:25], v[56:57], v[34:35], v[24:25] op_sel_hi:[1,0,1]
	s_waitcnt lgkmcnt(8)
	v_pk_mul_f32 v[34:35], v[22:23], v[178:179]
	v_pk_mul_f32 v[66:67], v[22:23], v[58:59]
	v_pk_fma_f32 v[34:35], v[24:25], v[180:181], v[34:35]
	v_pk_fma_f32 v[66:67], v[24:25], v[60:61], v[66:67]
	ds_read_b128 v[50:53], v38 offset:25600
	ds_read_b128 v[46:49], v38 offset:25344
	ds_read_b32 v62, v39 offset:26368
	ds_read_b128 v[54:57], v38 offset:25856
	ds_read_b128 v[58:61], v38 offset:26112
	v_add_f32_e32 v34, v34, v35
	v_add_f32_e32 v66, v66, v67
	v_pk_fma_f32 v[22:23], v[174:175], v[190:191], v[22:23] op_sel_hi:[1,0,1]
	v_add_f32_dpp v34, v34, v34 row_ror:1 row_mask:0xf bank_mask:0xf bound_ctrl:1
	v_add_f32_dpp v66, v66, v66 row_ror:1 row_mask:0xf bank_mask:0xf bound_ctrl:1
	v_pk_fma_f32 v[24:25], v[176:177], v[190:191], v[24:25] op_sel_hi:[1,0,1]
	v_add_f32_dpp v34, v34, v34 row_ror:2 row_mask:0xf bank_mask:0xf bound_ctrl:1
	v_add_f32_dpp v66, v66, v66 row_ror:2 row_mask:0xf bank_mask:0xf bound_ctrl:1
	ds_write2st64_b32 v41, v36, v66 offset0:12 offset1:13
	v_add_f32_dpp v34, v34, v34 row_ror:4 row_mask:0xf bank_mask:0xf bound_ctrl:1
	s_nop 0
	s_nop 0
	v_add_f32_dpp v34, v34, v34 row_ror:8 row_mask:0xf bank_mask:0xf bound_ctrl:1
	v_pk_fma_f32 v[22:23], v[182:183], v[34:35], v[22:23] op_sel_hi:[1,0,1]
	v_pk_fma_f32 v[24:25], v[184:185], v[34:35], v[24:25] op_sel_hi:[1,0,1]
	s_waitcnt lgkmcnt(7)
	v_pk_mul_f32 v[34:35], v[22:23], v[10:11]
	v_pk_mul_f32 v[36:37], v[22:23], v[186:187]
	v_pk_fma_f32 v[34:35], v[24:25], v[12:13], v[34:35]
	v_pk_fma_f32 v[36:37], v[24:25], v[188:189], v[36:37]
	ds_read_b128 v[178:181], v38 offset:27168
	ds_read_b128 v[174:177], v38 offset:26912
	ds_read_b32 v190, v39 offset:27936
	ds_read_b128 v[182:185], v38 offset:27424
	ds_read_b128 v[186:189], v38 offset:27680
	v_add_f32_e32 v34, v34, v35
	v_add_f32_e32 v36, v36, v37
	v_pk_fma_f32 v[22:23], v[6:7], v[28:29], v[22:23] op_sel_hi:[1,0,1]
	v_add_f32_dpp v34, v34, v34 row_ror:1 row_mask:0xf bank_mask:0xf bound_ctrl:1
	v_add_f32_dpp v36, v36, v36 row_ror:1 row_mask:0xf bank_mask:0xf bound_ctrl:1
	v_pk_fma_f32 v[24:25], v[8:9], v[28:29], v[24:25] op_sel_hi:[1,0,1]
	v_add_f32_dpp v34, v34, v34 row_ror:2 row_mask:0xf bank_mask:0xf bound_ctrl:1
	v_add_f32_dpp v36, v36, v36 row_ror:2 row_mask:0xf bank_mask:0xf bound_ctrl:1
	s_nop 0
	v_add_f32_dpp v34, v34, v34 row_ror:4 row_mask:0xf bank_mask:0xf bound_ctrl:1
	s_nop 0
	s_nop 0
	v_add_f32_dpp v34, v34, v34 row_ror:8 row_mask:0xf bank_mask:0xf bound_ctrl:1
	v_pk_fma_f32 v[22:23], v[14:15], v[34:35], v[22:23] op_sel_hi:[1,0,1]
	v_pk_fma_f32 v[24:25], v[16:17], v[34:35], v[24:25] op_sel_hi:[1,0,1]
	s_waitcnt lgkmcnt(7)
; template <int CTRL> __device__ __forceinline__ float dpp_f(float x) { return __int_as_float(__builtin_amdgcn_update_dpp(0, __float_as_int(x), CTRL, 0xf, 0xf, false)); }
; __device__ __forceinline__ void p8_scan(const Args& a, LAS unsigned char* lds) {
;     ...
; #pragma unroll 16
;                 for (int tt = 0; tt < TC; ++tt) {
;                     ScanOps n; scan_ld(n, bt + (tt + 1 < TC ? tt + 1 : tt) * SPITCH, jq4, myrow);
;                     __builtin_amdgcn_sched_barrier(0);
;                     f32x2 ta = S01 * o.al.lo, ty = S01 * o.wr.lo; ta = S23 * o.al.hi + ta; ty = S23 * o.wr.hi + ty;
;                     float pa = ta.x + ta.y, py = ty.x + ty.y;
;                     f32x2 kv01 = o.kv.lo * o.vi, kv23 = o.kv.hi * o.vi;
;     ...
;                     asm volatile("" : "+v"(kv01), "+v"(kv23), "+v"(vc));
;                     pa += dpp_f<0x121>(pa); py += dpp_f<0x121>(py); pa += dpp_f<0x122>(pa); py += dpp_f<0x122>(py);
;                     pa += dpp_f<0x124>(pa); pa += dpp_f<0x128>(pa);
;                     S01 = S01 * o.wv.lo + (o.be.lo * pa + kv01);
;                     S23 = S23 * o.wv.hi + (o.be.hi * pa + kv23);
;     ...
;                     __builtin_amdgcn_sched_barrier(0);
;                     o = n;
;                 }
	v_pk_mul_f32 v[66:67], v[22:23], v[18:19]
	v_pk_fma_f32 v[66:67], v[24:25], v[20:21], v[66:67]
	v_pk_mul_f32 v[22:23], v[22:23], v[2:3]
	v_pk_mul_f32 v[24:25], v[24:25], v[4:5]
	v_pk_mul_f32 v[34:35], v[22:23], v[50:51]
	v_pk_fma_f32 v[34:35], v[24:25], v[52:53], v[34:35]
	ds_read_b128 v[10:13], v38 offset:28736
	ds_read_b128 v[6:9], v38 offset:28480
	ds_read_b32 v28, v39 offset:29504
	ds_read_b128 v[14:17], v38 offset:28992
	ds_read_b128 v[18:21], v38 offset:29248
	v_add_f32_e32 v34, v34, v35
	v_add_f32_e32 v66, v66, v67
	v_pk_fma_f32 v[22:23], v[46:47], v[62:63], v[22:23] op_sel_hi:[1,0,1]
	v_add_f32_dpp v34, v34, v34 row_ror:1 row_mask:0xf bank_mask:0xf bound_ctrl:1
	v_add_f32_dpp v66, v66, v66 row_ror:1 row_mask:0xf bank_mask:0xf bound_ctrl:1
	v_pk_fma_f32 v[24:25], v[48:49], v[62:63], v[24:25] op_sel_hi:[1,0,1]
	v_add_f32_dpp v34, v34, v34 row_ror:2 row_mask:0xf bank_mask:0xf bound_ctrl:1
	v_add_f32_dpp v66, v66, v66 row_ror:2 row_mask:0xf bank_mask:0xf bound_ctrl:1
	ds_write2st64_b32 v41, v36, v66 offset0:14 offset1:15
	v_add_f32_dpp v34, v34, v34 row_ror:4 row_mask:0xf bank_mask:0xf bound_ctrl:1
	s_nop 0
	s_nop 0
	v_add_f32_dpp v34, v34, v34 row_ror:8 row_mask:0xf bank_mask:0xf bound_ctrl:1
	v_pk_fma_f32 v[22:23], v[54:55], v[34:35], v[22:23] op_sel_hi:[1,0,1]
	v_pk_fma_f32 v[24:25], v[56:57], v[34:35], v[24:25] op_sel_hi:[1,0,1]
	s_waitcnt lgkmcnt(7)
	v_pk_mul_f32 v[34:35], v[22:23], v[178:179]
	v_pk_mul_f32 v[36:37], v[22:23], v[58:59]
	v_pk_fma_f32 v[34:35], v[24:25], v[180:181], v[34:35]
	v_pk_fma_f32 v[36:37], v[24:25], v[60:61], v[36:37]
	ds_read_b128 v[50:53], v38 offset:30304
	ds_read_b128 v[46:49], v38 offset:30048
	ds_read_b32 v62, v39 offset:31072
	ds_read_b128 v[54:57], v38 offset:30560
	ds_read_b128 v[58:61], v38 offset:30816
	v_add_f32_e32 v34, v34, v35
	v_add_f32_e32 v36, v36, v37
	v_pk_fma_f32 v[22:23], v[174:175], v[190:191], v[22:23] op_sel_hi:[1,0,1]
	v_add_f32_dpp v34, v34, v34 row_ror:1 row_mask:0xf bank_mask:0xf bound_ctrl:1
	v_add_f32_dpp v36, v36, v36 row_ror:1 row_mask:0xf bank_mask:0xf bound_ctrl:1
	v_pk_fma_f32 v[24:25], v[176:177], v[190:191], v[24:25] op_sel_hi:[1,0,1]
	v_add_f32_dpp v34, v34, v34 row_ror:2 row_mask:0xf bank_mask:0xf bound_ctrl:1
	v_add_f32_dpp v36, v36, v36 row_ror:2 row_mask:0xf bank_mask:0xf bound_ctrl:1
	s_nop 0
	v_add_f32_dpp v34, v34, v34 row_ror:4 row_mask:0xf bank_mask:0xf bound_ctrl:1
	s_nop 0
	s_nop 0
	v_add_f32_dpp v34, v34, v34 row_ror:8 row_mask:0xf bank_mask:0xf bound_ctrl:1
	v_pk_fma_f32 v[22:23], v[182:183], v[34:35], v[22:23] op_sel_hi:[1,0,1]
	v_pk_fma_f32 v[24:25], v[184:185], v[34:35], v[24:25] op_sel_hi:[1,0,1]
	s_waitcnt lgkmcnt(7)
	v_pk_mul_f32 v[34:35], v[22:23], v[10:11]
	v_pk_mul_f32 v[66:67], v[22:23], v[186:187]
	v_pk_fma_f32 v[34:35], v[24:25], v[12:13], v[34:35]
	v_pk_fma_f32 v[66:67], v[24:25], v[188:189], v[66:67]
	ds_read_b128 v[178:181], v38 offset:31872
	ds_read_b128 v[174:177], v38 offset:31616
	ds_read_b32 v190, v39 offset:32640
	ds_read_b128 v[182:185], v38 offset:32128
	ds_read_b128 v[186:189], v38 offset:32384
	v_add_f32_e32 v34, v34, v35
	v_add_f32_e32 v66, v66, v67
	v_pk_fma_f32 v[22:23], v[6:7], v[28:29], v[22:23] op_sel_hi:[1,0,1]
	v_add_f32_dpp v34, v34, v34 row_ror:1 row_mask:0xf bank_mask:0xf bound_ctrl:1
	v_add_f32_dpp v66, v66, v66 row_ror:1 row_mask:0xf bank_mask:0xf bound_ctrl:1
	v_pk_fma_f32 v[24:25], v[8:9], v[28:29], v[24:25] op_sel_hi:[1,0,1]
	v_add_f32_dpp v34, v34, v34 row_ror:2 row_mask:0xf bank_mask:0xf bound_ctrl:1
	v_add_f32_dpp v66, v66, v66 row_ror:2 row_mask:0xf bank_mask:0xf bound_ctrl:1
	ds_write2st64_b32 v41, v36, v66 offset0:16 offset1:17
	v_add_f32_dpp v34, v34, v34 row_ror:4 row_mask:0xf bank_mask:0xf bound_ctrl:1
	s_nop 0
	s_nop 0
	v_add_f32_dpp v34, v34, v34 row_ror:8 row_mask:0xf bank_mask:0xf bound_ctrl:1
	v_pk_fma_f32 v[22:23], v[14:15], v[34:35], v[22:23] op_sel_hi:[1,0,1]
	v_pk_fma_f32 v[24:25], v[16:17], v[34:35], v[24:25] op_sel_hi:[1,0,1]
	s_waitcnt lgkmcnt(7)
	v_pk_mul_f32 v[34:35], v[22:23], v[50:51]
	v_pk_mul_f32 v[36:37], v[22:23], v[18:19]
	v_pk_fma_f32 v[34:35], v[24:25], v[52:53], v[34:35]
	v_pk_fma_f32 v[36:37], v[24:25], v[20:21], v[36:37]
	ds_read_b128 v[10:13], v38 offset:33440
	ds_read_b128 v[6:9], v38 offset:33184
	ds_read_b32 v28, v39 offset:34208
	ds_read_b128 v[14:17], v38 offset:33696
	ds_read_b128 v[18:21], v38 offset:33952
	v_add_f32_e32 v34, v34, v35
	v_add_f32_e32 v36, v36, v37
	v_pk_fma_f32 v[22:23], v[46:47], v[62:63], v[22:23] op_sel_hi:[1,0,1]
	v_add_f32_dpp v34, v34, v34 row_ror:1 row_mask:0xf bank_mask:0xf bound_ctrl:1
	v_add_f32_dpp v36, v36, v36 row_ror:1 row_mask:0xf bank_mask:0xf bound_ctrl:1
	v_pk_fma_f32 v[24:25], v[48:49], v[62:63], v[24:25] op_sel_hi:[1,0,1]
	v_add_f32_dpp v34, v34, v34 row_ror:2 row_mask:0xf bank_mask:0xf bound_ctrl:1
	v_add_f32_dpp v36, v36, v36 row_ror:2 row_mask:0xf bank_mask:0xf bound_ctrl:1
	s_nop 0
	v_add_f32_dpp v34, v34, v34 row_ror:4 row_mask:0xf bank_mask:0xf bound_ctrl:1
	s_nop 0
	s_nop 0
	v_add_f32_dpp v34, v34, v34 row_ror:8 row_mask:0xf bank_mask:0xf bound_ctrl:1
	v_pk_fma_f32 v[22:23], v[54:55], v[34:35], v[22:23] op_sel_hi:[1,0,1]
	v_pk_fma_f32 v[24:25], v[56:57], v[34:35], v[24:25] op_sel_hi:[1,0,1]
	s_waitcnt lgkmcnt(7)
; template <int CTRL> __device__ __forceinline__ float dpp_f(float x) { return __int_as_float(__builtin_amdgcn_update_dpp(0, __float_as_int(x), CTRL, 0xf, 0xf, false)); }
; __device__ __forceinline__ void p8_scan(const Args& a, LAS unsigned char* lds) {
;     ...
; #pragma unroll 16
;                 for (int tt = 0; tt < TC; ++tt) {
;                     ScanOps n; scan_ld(n, bt + (tt + 1 < TC ? tt + 1 : tt) * SPITCH, jq4, myrow);
;                     __builtin_amdgcn_sched_barrier(0);
;                     f32x2 ta = S01 * o.al.lo, ty = S01 * o.wr.lo; ta = S23 * o.al.hi + ta; ty = S23 * o.wr.hi + ty;
;                     float pa = ta.x + ta.y, py = ty.x + ty.y;
;                     f32x2 kv01 = o.kv.lo * o.vi, kv23 = o.kv.hi * o.vi;
;     ...
;                     asm volatile("" : "+v"(kv01), "+v"(kv23), "+v"(vc));
;                     pa += dpp_f<0x121>(pa); py += dpp_f<0x121>(py); pa += dpp_f<0x122>(pa); py += dpp_f<0x122>(py);
;                     pa += dpp_f<0x124>(pa); pa += dpp_f<0x128>(pa);
;                     S01 = S01 * o.wv.lo + (o.be.lo * pa + kv01);
;                     S23 = S23 * o.wv.hi + (o.be.hi * pa + kv23);
;     ...
;                     __builtin_amdgcn_sched_barrier(0);
;                     o = n;
;                 }
	v_pk_mul_f32 v[34:35], v[22:23], v[178:179]
	v_pk_mul_f32 v[66:67], v[22:23], v[58:59]
	v_pk_fma_f32 v[34:35], v[24:25], v[180:181], v[34:35]
	v_pk_fma_f32 v[66:67], v[24:25], v[60:61], v[66:67]
	ds_read_b128 v[50:53], v38 offset:35008
	ds_read_b128 v[46:49], v38 offset:34752
	ds_read_b32 v62, v39 offset:35776
	ds_read_b128 v[54:57], v38 offset:35264
	ds_read_b128 v[58:61], v38 offset:35520
	v_add_f32_e32 v34, v34, v35
	v_add_f32_e32 v66, v66, v67
	v_pk_fma_f32 v[22:23], v[174:175], v[190:191], v[22:23] op_sel_hi:[1,0,1]
	v_add_f32_dpp v34, v34, v34 row_ror:1 row_mask:0xf bank_mask:0xf bound_ctrl:1
	v_add_f32_dpp v66, v66, v66 row_ror:1 row_mask:0xf bank_mask:0xf bound_ctrl:1
	v_pk_fma_f32 v[24:25], v[176:177], v[190:191], v[24:25] op_sel_hi:[1,0,1]
	v_add_f32_dpp v34, v34, v34 row_ror:2 row_mask:0xf bank_mask:0xf bound_ctrl:1
	v_add_f32_dpp v66, v66, v66 row_ror:2 row_mask:0xf bank_mask:0xf bound_ctrl:1
	ds_write2st64_b32 v41, v36, v66 offset0:18 offset1:19
	v_add_f32_dpp v34, v34, v34 row_ror:4 row_mask:0xf bank_mask:0xf bound_ctrl:1
	s_nop 0
	s_nop 0
	v_add_f32_dpp v34, v34, v34 row_ror:8 row_mask:0xf bank_mask:0xf bound_ctrl:1
	v_pk_fma_f32 v[22:23], v[182:183], v[34:35], v[22:23] op_sel_hi:[1,0,1]
	v_pk_fma_f32 v[24:25], v[184:185], v[34:35], v[24:25] op_sel_hi:[1,0,1]
	s_waitcnt lgkmcnt(7)
	v_pk_mul_f32 v[34:35], v[22:23], v[10:11]
	v_pk_mul_f32 v[36:37], v[22:23], v[186:187]
	v_pk_fma_f32 v[34:35], v[24:25], v[12:13], v[34:35]
	v_pk_fma_f32 v[36:37], v[24:25], v[188:189], v[36:37]
	ds_read_b128 v[178:181], v38 offset:36576
	ds_read_b128 v[174:177], v38 offset:36320
	ds_read_b32 v190, v39 offset:37344
	ds_read_b128 v[192:195], v38 offset:36064
	ds_read_b128 v[182:185], v38 offset:36832
	ds_read_b128 v[186:189], v38 offset:37088
	v_add_f32_e32 v34, v34, v35
	v_add_f32_e32 v36, v36, v37
	v_pk_fma_f32 v[22:23], v[6:7], v[28:29], v[22:23] op_sel_hi:[1,0,1]
	v_add_f32_dpp v34, v34, v34 row_ror:1 row_mask:0xf bank_mask:0xf bound_ctrl:1
	v_add_f32_dpp v36, v36, v36 row_ror:1 row_mask:0xf bank_mask:0xf bound_ctrl:1
	v_pk_fma_f32 v[24:25], v[8:9], v[28:29], v[24:25] op_sel_hi:[1,0,1]
	v_add_f32_dpp v34, v34, v34 row_ror:2 row_mask:0xf bank_mask:0xf bound_ctrl:1
	v_add_f32_dpp v36, v36, v36 row_ror:2 row_mask:0xf bank_mask:0xf bound_ctrl:1
	s_nop 0
	v_add_f32_dpp v34, v34, v34 row_ror:4 row_mask:0xf bank_mask:0xf bound_ctrl:1
	s_nop 0
	s_nop 0
	v_add_f32_dpp v34, v34, v34 row_ror:8 row_mask:0xf bank_mask:0xf bound_ctrl:1
	v_pk_fma_f32 v[22:23], v[14:15], v[34:35], v[22:23] op_sel_hi:[1,0,1]
	v_pk_fma_f32 v[24:25], v[16:17], v[34:35], v[24:25] op_sel_hi:[1,0,1]
	s_waitcnt lgkmcnt(8)
	v_pk_mul_f32 v[34:35], v[22:23], v[50:51]
	v_pk_mul_f32 v[66:67], v[22:23], v[18:19]
	v_pk_fma_f32 v[34:35], v[24:25], v[52:53], v[34:35]
	v_pk_fma_f32 v[66:67], v[24:25], v[20:21], v[66:67]
	ds_read_b128 v[10:13], v38 offset:38144
	ds_read_b128 v[6:9], v38 offset:37888
	ds_read_b32 v28, v39 offset:38912
	ds_read_b128 v[14:17], v38 offset:38400
	ds_read_b128 v[18:21], v38 offset:38656
	v_add_f32_e32 v34, v34, v35
	v_add_f32_e32 v66, v66, v67
	v_pk_fma_f32 v[22:23], v[46:47], v[62:63], v[22:23] op_sel_hi:[1,0,1]
	v_add_f32_dpp v34, v34, v34 row_ror:1 row_mask:0xf bank_mask:0xf bound_ctrl:1
	v_add_f32_dpp v66, v66, v66 row_ror:1 row_mask:0xf bank_mask:0xf bound_ctrl:1
	v_pk_fma_f32 v[24:25], v[48:49], v[62:63], v[24:25] op_sel_hi:[1,0,1]
	v_add_f32_dpp v34, v34, v34 row_ror:2 row_mask:0xf bank_mask:0xf bound_ctrl:1
	v_add_f32_dpp v66, v66, v66 row_ror:2 row_mask:0xf bank_mask:0xf bound_ctrl:1
	ds_write2st64_b32 v41, v36, v66 offset0:20 offset1:21
	v_add_f32_dpp v34, v34, v34 row_ror:4 row_mask:0xf bank_mask:0xf bound_ctrl:1
	s_nop 0
	s_nop 0
	v_add_f32_dpp v34, v34, v34 row_ror:8 row_mask:0xf bank_mask:0xf bound_ctrl:1
	v_pk_fma_f32 v[22:23], v[54:55], v[34:35], v[22:23] op_sel_hi:[1,0,1]
	v_pk_fma_f32 v[24:25], v[56:57], v[34:35], v[24:25] op_sel_hi:[1,0,1]
	s_waitcnt lgkmcnt(7)
	v_pk_mul_f32 v[34:35], v[22:23], v[178:179]
	v_pk_mul_f32 v[36:37], v[22:23], v[58:59]
	v_pk_fma_f32 v[34:35], v[24:25], v[180:181], v[34:35]
	v_pk_fma_f32 v[36:37], v[24:25], v[60:61], v[36:37]
	ds_read_b128 v[50:53], v38 offset:39712
	ds_read_b128 v[46:49], v38 offset:39456
	ds_read_b32 v62, v39 offset:40480
	ds_read_b128 v[54:57], v38 offset:39968
	ds_read_b128 v[58:61], v38 offset:40224
	v_add_f32_e32 v34, v34, v35
	v_add_f32_e32 v36, v36, v37
	v_pk_fma_f32 v[22:23], v[174:175], v[190:191], v[22:23] op_sel_hi:[1,0,1]
	v_add_f32_dpp v34, v34, v34 row_ror:1 row_mask:0xf bank_mask:0xf bound_ctrl:1
	v_add_f32_dpp v36, v36, v36 row_ror:1 row_mask:0xf bank_mask:0xf bound_ctrl:1
	v_pk_fma_f32 v[24:25], v[176:177], v[190:191], v[24:25] op_sel_hi:[1,0,1]
	v_add_f32_dpp v34, v34, v34 row_ror:2 row_mask:0xf bank_mask:0xf bound_ctrl:1
	v_add_f32_dpp v36, v36, v36 row_ror:2 row_mask:0xf bank_mask:0xf bound_ctrl:1
	s_nop 0
	v_add_f32_dpp v34, v34, v34 row_ror:4 row_mask:0xf bank_mask:0xf bound_ctrl:1
	s_nop 0
	s_nop 0
	v_add_f32_dpp v34, v34, v34 row_ror:8 row_mask:0xf bank_mask:0xf bound_ctrl:1
	v_pk_fma_f32 v[22:23], v[182:183], v[34:35], v[22:23] op_sel_hi:[1,0,1]
	v_pk_fma_f32 v[24:25], v[184:185], v[34:35], v[24:25] op_sel_hi:[1,0,1]
	s_waitcnt lgkmcnt(7)
; template <int CTRL> __device__ __forceinline__ float dpp_f(float x) { return __int_as_float(__builtin_amdgcn_update_dpp(0, __float_as_int(x), CTRL, 0xf, 0xf, false)); }
; __device__ __forceinline__ void p8_scan(const Args& a, LAS unsigned char* lds) {
;     ...
; #pragma unroll 16
;                 for (int tt = 0; tt < TC; ++tt) {
;                     ScanOps n; scan_ld(n, bt + (tt + 1 < TC ? tt + 1 : tt) * SPITCH, jq4, myrow);
;                     __builtin_amdgcn_sched_barrier(0);
;                     f32x2 ta = S01 * o.al.lo, ty = S01 * o.wr.lo; ta = S23 * o.al.hi + ta; ty = S23 * o.wr.hi + ty;
;                     float pa = ta.x + ta.y, py = ty.x + ty.y;
;                     f32x2 kv01 = o.kv.lo * o.vi, kv23 = o.kv.hi * o.vi;
;     ...
;                     asm volatile("" : "+v"(kv01), "+v"(kv23), "+v"(vc));
;                     pa += dpp_f<0x121>(pa); py += dpp_f<0x121>(py); pa += dpp_f<0x122>(pa); py += dpp_f<0x122>(py);
;                     pa += dpp_f<0x124>(pa); pa += dpp_f<0x128>(pa);
;                     S01 = S01 * o.wv.lo + (o.be.lo * pa + kv01);
;                     S23 = S23 * o.wv.hi + (o.be.hi * pa + kv23);
;     ...
;                     __builtin_amdgcn_sched_barrier(0);
;                     o = n;
;                 }
	v_pk_mul_f32 v[66:67], v[22:23], v[186:187]
	v_pk_fma_f32 v[66:67], v[24:25], v[188:189], v[66:67]
	v_pk_mul_f32 v[22:23], v[22:23], v[192:193]
	v_pk_mul_f32 v[24:25], v[24:25], v[194:195]
	v_pk_mul_f32 v[34:35], v[22:23], v[10:11]
	v_pk_fma_f32 v[34:35], v[24:25], v[12:13], v[34:35]
	ds_read_b128 v[178:181], v38 offset:41280
	ds_read_b128 v[174:177], v38 offset:41024
	ds_read_b32 v190, v39 offset:42048
	ds_read_b128 v[182:185], v38 offset:41536
	ds_read_b128 v[186:189], v38 offset:41792
	v_add_f32_e32 v34, v34, v35
	v_add_f32_e32 v66, v66, v67
	v_pk_fma_f32 v[22:23], v[6:7], v[28:29], v[22:23] op_sel_hi:[1,0,1]
	v_add_f32_dpp v34, v34, v34 row_ror:1 row_mask:0xf bank_mask:0xf bound_ctrl:1
	v_add_f32_dpp v66, v66, v66 row_ror:1 row_mask:0xf bank_mask:0xf bound_ctrl:1
	v_pk_fma_f32 v[24:25], v[8:9], v[28:29], v[24:25] op_sel_hi:[1,0,1]
	v_add_f32_dpp v34, v34, v34 row_ror:2 row_mask:0xf bank_mask:0xf bound_ctrl:1
	v_add_f32_dpp v66, v66, v66 row_ror:2 row_mask:0xf bank_mask:0xf bound_ctrl:1
	ds_write2st64_b32 v41, v36, v66 offset0:22 offset1:23
	v_add_f32_dpp v34, v34, v34 row_ror:4 row_mask:0xf bank_mask:0xf bound_ctrl:1
	s_nop 0
	s_nop 0
	v_add_f32_dpp v34, v34, v34 row_ror:8 row_mask:0xf bank_mask:0xf bound_ctrl:1
	v_pk_fma_f32 v[22:23], v[14:15], v[34:35], v[22:23] op_sel_hi:[1,0,1]
	v_pk_fma_f32 v[24:25], v[16:17], v[34:35], v[24:25] op_sel_hi:[1,0,1]
	s_waitcnt lgkmcnt(7)
	v_pk_mul_f32 v[34:35], v[22:23], v[50:51]
	v_pk_mul_f32 v[36:37], v[22:23], v[18:19]
	v_pk_fma_f32 v[34:35], v[24:25], v[52:53], v[34:35]
	v_pk_fma_f32 v[36:37], v[24:25], v[20:21], v[36:37]
	ds_read_b128 v[10:13], v38 offset:42848
	ds_read_b128 v[6:9], v38 offset:42592
	ds_read_b32 v28, v39 offset:43616
	ds_read_b128 v[14:17], v38 offset:43104
	ds_read_b128 v[18:21], v38 offset:43360
	v_add_f32_e32 v34, v34, v35
	v_add_f32_e32 v36, v36, v37
	v_pk_fma_f32 v[22:23], v[46:47], v[62:63], v[22:23] op_sel_hi:[1,0,1]
	v_add_f32_dpp v34, v34, v34 row_ror:1 row_mask:0xf bank_mask:0xf bound_ctrl:1
	v_add_f32_dpp v36, v36, v36 row_ror:1 row_mask:0xf bank_mask:0xf bound_ctrl:1
	v_pk_fma_f32 v[24:25], v[48:49], v[62:63], v[24:25] op_sel_hi:[1,0,1]
	v_add_f32_dpp v34, v34, v34 row_ror:2 row_mask:0xf bank_mask:0xf bound_ctrl:1
	v_add_f32_dpp v36, v36, v36 row_ror:2 row_mask:0xf bank_mask:0xf bound_ctrl:1
	s_nop 0
	v_add_f32_dpp v34, v34, v34 row_ror:4 row_mask:0xf bank_mask:0xf bound_ctrl:1
	s_nop 0
	s_nop 0
	v_add_f32_dpp v34, v34, v34 row_ror:8 row_mask:0xf bank_mask:0xf bound_ctrl:1
	v_pk_fma_f32 v[22:23], v[54:55], v[34:35], v[22:23] op_sel_hi:[1,0,1]
	v_pk_fma_f32 v[24:25], v[56:57], v[34:35], v[24:25] op_sel_hi:[1,0,1]
	s_waitcnt lgkmcnt(7)
	v_pk_mul_f32 v[34:35], v[22:23], v[178:179]
	v_pk_mul_f32 v[66:67], v[22:23], v[58:59]
	v_pk_fma_f32 v[34:35], v[24:25], v[180:181], v[34:35]
	v_pk_fma_f32 v[66:67], v[24:25], v[60:61], v[66:67]
	ds_read_b128 v[50:53], v38 offset:44416
	ds_read_b128 v[46:49], v38 offset:44160
	ds_read_b32 v62, v39 offset:45184
	ds_read_b128 v[54:57], v38 offset:44672
	ds_read_b128 v[58:61], v38 offset:44928
	v_add_f32_e32 v34, v34, v35
	v_add_f32_e32 v66, v66, v67
	v_pk_fma_f32 v[22:23], v[174:175], v[190:191], v[22:23] op_sel_hi:[1,0,1]
	v_add_f32_dpp v34, v34, v34 row_ror:1 row_mask:0xf bank_mask:0xf bound_ctrl:1
	v_add_f32_dpp v66, v66, v66 row_ror:1 row_mask:0xf bank_mask:0xf bound_ctrl:1
	v_pk_fma_f32 v[24:25], v[176:177], v[190:191], v[24:25] op_sel_hi:[1,0,1]
	v_add_f32_dpp v34, v34, v34 row_ror:2 row_mask:0xf bank_mask:0xf bound_ctrl:1
	v_add_f32_dpp v66, v66, v66 row_ror:2 row_mask:0xf bank_mask:0xf bound_ctrl:1
	ds_write2st64_b32 v41, v36, v66 offset0:24 offset1:25
	v_add_f32_dpp v34, v34, v34 row_ror:4 row_mask:0xf bank_mask:0xf bound_ctrl:1
	s_nop 0
	s_nop 0
	v_add_f32_dpp v34, v34, v34 row_ror:8 row_mask:0xf bank_mask:0xf bound_ctrl:1
	v_pk_fma_f32 v[22:23], v[182:183], v[34:35], v[22:23] op_sel_hi:[1,0,1]
	v_pk_fma_f32 v[24:25], v[184:185], v[34:35], v[24:25] op_sel_hi:[1,0,1]
	s_waitcnt lgkmcnt(7)
	v_pk_mul_f32 v[34:35], v[22:23], v[10:11]
	v_pk_mul_f32 v[36:37], v[22:23], v[186:187]
	v_pk_fma_f32 v[34:35], v[24:25], v[12:13], v[34:35]
	v_pk_fma_f32 v[36:37], v[24:25], v[188:189], v[36:37]
	ds_read_b128 v[178:181], v38 offset:45984
	ds_read_b128 v[174:177], v38 offset:45728
	ds_read_b32 v190, v39 offset:46752
	ds_read_b128 v[182:185], v38 offset:46240
	ds_read_b128 v[186:189], v38 offset:46496
	v_add_f32_e32 v34, v34, v35
	v_add_f32_e32 v36, v36, v37
	v_pk_fma_f32 v[22:23], v[6:7], v[28:29], v[22:23] op_sel_hi:[1,0,1]
	v_add_f32_dpp v34, v34, v34 row_ror:1 row_mask:0xf bank_mask:0xf bound_ctrl:1
	v_add_f32_dpp v36, v36, v36 row_ror:1 row_mask:0xf bank_mask:0xf bound_ctrl:1
	v_pk_fma_f32 v[24:25], v[8:9], v[28:29], v[24:25] op_sel_hi:[1,0,1]
	v_add_f32_dpp v34, v34, v34 row_ror:2 row_mask:0xf bank_mask:0xf bound_ctrl:1
	v_add_f32_dpp v36, v36, v36 row_ror:2 row_mask:0xf bank_mask:0xf bound_ctrl:1
	s_nop 0
	v_add_f32_dpp v34, v34, v34 row_ror:4 row_mask:0xf bank_mask:0xf bound_ctrl:1
	s_nop 0
	s_nop 0
	v_add_f32_dpp v34, v34, v34 row_ror:8 row_mask:0xf bank_mask:0xf bound_ctrl:1
	v_pk_fma_f32 v[22:23], v[14:15], v[34:35], v[22:23] op_sel_hi:[1,0,1]
	v_pk_fma_f32 v[24:25], v[16:17], v[34:35], v[24:25] op_sel_hi:[1,0,1]
	s_waitcnt lgkmcnt(7)
; #define LAS __attribute__((address_space(3)))
; template <int CTRL> __device__ __forceinline__ float dpp_f(float x) { return __int_as_float(__builtin_amdgcn_update_dpp(0, __float_as_int(x), CTRL, 0xf, 0xf, false)); }
; __device__ __forceinline__ void p8_scan(const Args& a, LAS unsigned char* lds) {
;     ...
;             for (int c = 0; c < T / TC; ++c) {
;                 const int cur = c & 1;
;                 const LAS float* bt = buf + cur * TC * SPITCH;
;                 LAS float* yd = holds_y ? (ybuf + cur * TC * 64 + 4 * (4 * w + (lane >> 4)) + ((lane & 15) >> 2)) : (dump + lane);
;                 ScanOps o; scan_ld(o, bt, jq4, myrow);
; #pragma unroll 16
;                 for (int tt = 0; tt < TC; ++tt) {
;                     ScanOps n; scan_ld(n, bt + (tt + 1 < TC ? tt + 1 : tt) * SPITCH, jq4, myrow);
;                     __builtin_amdgcn_sched_barrier(0);
;                     f32x2 ta = S01 * o.al.lo, ty = S01 * o.wr.lo; ta = S23 * o.al.hi + ta; ty = S23 * o.wr.hi + ty;
;                     float pa = ta.x + ta.y, py = ty.x + ty.y;
;                     f32x2 kv01 = o.kv.lo * o.vi, kv23 = o.kv.hi * o.vi;
;     ...
;                     asm volatile("" : "+v"(kv01), "+v"(kv23), "+v"(vc));
;                     pa += dpp_f<0x121>(pa); py += dpp_f<0x121>(py); pa += dpp_f<0x122>(pa); py += dpp_f<0x122>(py);
;                     pa += dpp_f<0x124>(pa); pa += dpp_f<0x128>(pa);
;                     S01 = S01 * o.wv.lo + (o.be.lo * pa + kv01);
;                     S23 = S23 * o.wv.hi + (o.be.hi * pa + kv23);
;     ...
;                     __builtin_amdgcn_sched_barrier(0);
;                     o = n;
;                 }
;                 __syncthreads();
	v_pk_mul_f32 v[34:35], v[22:23], v[50:51]
	v_pk_mul_f32 v[66:67], v[22:23], v[18:19]
	v_pk_fma_f32 v[34:35], v[24:25], v[52:53], v[34:35]
	v_pk_fma_f32 v[66:67], v[24:25], v[20:21], v[66:67]
	ds_read_b128 v[10:13], v38 offset:47552
	ds_read_b128 v[6:9], v38 offset:47296
	ds_read_b32 v28, v39 offset:48320
	ds_read_b128 v[14:17], v38 offset:47808
	ds_read_b128 v[18:21], v38 offset:48064
	v_add_f32_e32 v34, v34, v35
	v_add_f32_e32 v66, v66, v67
	v_pk_fma_f32 v[22:23], v[46:47], v[62:63], v[22:23] op_sel_hi:[1,0,1]
	v_add_f32_dpp v34, v34, v34 row_ror:1 row_mask:0xf bank_mask:0xf bound_ctrl:1
	v_add_f32_dpp v66, v66, v66 row_ror:1 row_mask:0xf bank_mask:0xf bound_ctrl:1
	v_pk_fma_f32 v[24:25], v[48:49], v[62:63], v[24:25] op_sel_hi:[1,0,1]
	v_add_f32_dpp v34, v34, v34 row_ror:2 row_mask:0xf bank_mask:0xf bound_ctrl:1
	v_add_f32_dpp v66, v66, v66 row_ror:2 row_mask:0xf bank_mask:0xf bound_ctrl:1
	ds_write2st64_b32 v41, v36, v66 offset0:26 offset1:27
	v_add_f32_dpp v34, v34, v34 row_ror:4 row_mask:0xf bank_mask:0xf bound_ctrl:1
	s_nop 0
	s_nop 0
	v_add_f32_dpp v34, v34, v34 row_ror:8 row_mask:0xf bank_mask:0xf bound_ctrl:1
	v_pk_fma_f32 v[22:23], v[54:55], v[34:35], v[22:23] op_sel_hi:[1,0,1]
	v_pk_fma_f32 v[24:25], v[56:57], v[34:35], v[24:25] op_sel_hi:[1,0,1]
	s_waitcnt lgkmcnt(7)
	v_pk_mul_f32 v[34:35], v[22:23], v[178:179]
	v_pk_mul_f32 v[36:37], v[22:23], v[58:59]
	v_pk_fma_f32 v[34:35], v[24:25], v[180:181], v[34:35]
	v_pk_fma_f32 v[36:37], v[24:25], v[60:61], v[36:37]
	ds_read_b128 v[50:53], v38 offset:49120
	ds_read_b128 v[46:49], v38 offset:48864
	ds_read_b32 v62, v39 offset:49888
	ds_read_b128 v[42:45], v38 offset:48608
	ds_read_b128 v[54:57], v38 offset:49376
	ds_read_b128 v[58:61], v38 offset:49632
	v_add_f32_e32 v34, v34, v35
	v_add_f32_e32 v36, v36, v37
	v_pk_fma_f32 v[22:23], v[174:175], v[190:191], v[22:23] op_sel_hi:[1,0,1]
	v_add_f32_dpp v34, v34, v34 row_ror:1 row_mask:0xf bank_mask:0xf bound_ctrl:1
	v_add_f32_dpp v36, v36, v36 row_ror:1 row_mask:0xf bank_mask:0xf bound_ctrl:1
	v_pk_fma_f32 v[24:25], v[176:177], v[190:191], v[24:25] op_sel_hi:[1,0,1]
	v_add_f32_dpp v34, v34, v34 row_ror:2 row_mask:0xf bank_mask:0xf bound_ctrl:1
	v_add_f32_dpp v36, v36, v36 row_ror:2 row_mask:0xf bank_mask:0xf bound_ctrl:1
	s_nop 0
	v_add_f32_dpp v34, v34, v34 row_ror:4 row_mask:0xf bank_mask:0xf bound_ctrl:1
	s_nop 0
	s_nop 0
	v_add_f32_dpp v34, v34, v34 row_ror:8 row_mask:0xf bank_mask:0xf bound_ctrl:1
	v_pk_fma_f32 v[22:23], v[182:183], v[34:35], v[22:23] op_sel_hi:[1,0,1]
	v_pk_fma_f32 v[24:25], v[184:185], v[34:35], v[24:25] op_sel_hi:[1,0,1]
	s_waitcnt lgkmcnt(8)
	v_pk_mul_f32 v[34:35], v[22:23], v[10:11]
	v_pk_mul_f32 v[66:67], v[22:23], v[186:187]
	v_pk_fma_f32 v[34:35], v[24:25], v[12:13], v[34:35]
	v_pk_fma_f32 v[66:67], v[24:25], v[188:189], v[66:67]
	v_add_f32_e32 v34, v34, v35
	v_add_f32_e32 v66, v66, v67
	v_pk_fma_f32 v[22:23], v[6:7], v[28:29], v[22:23] op_sel_hi:[1,0,1]
	v_add_f32_dpp v34, v34, v34 row_ror:1 row_mask:0xf bank_mask:0xf bound_ctrl:1
	v_add_f32_dpp v66, v66, v66 row_ror:1 row_mask:0xf bank_mask:0xf bound_ctrl:1
	v_pk_fma_f32 v[24:25], v[8:9], v[28:29], v[24:25] op_sel_hi:[1,0,1]
	v_add_f32_dpp v34, v34, v34 row_ror:2 row_mask:0xf bank_mask:0xf bound_ctrl:1
	v_add_f32_dpp v66, v66, v66 row_ror:2 row_mask:0xf bank_mask:0xf bound_ctrl:1
	ds_write2st64_b32 v41, v36, v66 offset0:28 offset1:29
	v_add_f32_dpp v34, v34, v34 row_ror:4 row_mask:0xf bank_mask:0xf bound_ctrl:1
	s_nop 0
	s_nop 0
	v_add_f32_dpp v34, v34, v34 row_ror:8 row_mask:0xf bank_mask:0xf bound_ctrl:1
	v_pk_fma_f32 v[22:23], v[14:15], v[34:35], v[22:23] op_sel_hi:[1,0,1]
	v_pk_fma_f32 v[24:25], v[16:17], v[34:35], v[24:25] op_sel_hi:[1,0,1]
	s_waitcnt lgkmcnt(0)
	v_pk_mul_f32 v[34:35], v[22:23], v[50:51]
	v_pk_mul_f32 v[36:37], v[22:23], v[18:19]
	v_pk_fma_f32 v[34:35], v[24:25], v[52:53], v[34:35]
	v_pk_fma_f32 v[36:37], v[24:25], v[20:21], v[36:37]
	v_add_f32_e32 v34, v34, v35
	v_add_f32_e32 v36, v36, v37
	v_pk_fma_f32 v[22:23], v[46:47], v[62:63], v[22:23] op_sel_hi:[1,0,1]
	v_add_f32_dpp v34, v34, v34 row_ror:1 row_mask:0xf bank_mask:0xf bound_ctrl:1
	v_add_f32_dpp v36, v36, v36 row_ror:1 row_mask:0xf bank_mask:0xf bound_ctrl:1
	v_pk_fma_f32 v[24:25], v[48:49], v[62:63], v[24:25] op_sel_hi:[1,0,1]
	v_add_f32_dpp v34, v34, v34 row_ror:2 row_mask:0xf bank_mask:0xf bound_ctrl:1
	v_add_f32_dpp v36, v36, v36 row_ror:2 row_mask:0xf bank_mask:0xf bound_ctrl:1
	s_nop 0
	v_add_f32_dpp v34, v34, v34 row_ror:4 row_mask:0xf bank_mask:0xf bound_ctrl:1
	s_nop 0
	s_nop 0
	v_add_f32_dpp v34, v34, v34 row_ror:8 row_mask:0xf bank_mask:0xf bound_ctrl:1
	v_pk_fma_f32 v[22:23], v[54:55], v[34:35], v[22:23] op_sel_hi:[1,0,1]
	v_pk_fma_f32 v[24:25], v[56:57], v[34:35], v[24:25] op_sel_hi:[1,0,1]
	v_pk_mul_f32 v[66:67], v[22:23], v[58:59]
	v_pk_fma_f32 v[66:67], v[24:25], v[60:61], v[66:67]
	v_add_f32_e32 v66, v66, v67
	v_pk_mul_f32 v[22:23], v[22:23], v[42:43]
	v_pk_mul_f32 v[24:25], v[24:25], v[44:45]
	v_add_f32_dpp v66, v66, v66 row_ror:1 row_mask:0xf bank_mask:0xf bound_ctrl:1
	s_nop 0
	s_nop 0
	v_add_f32_dpp v66, v66, v66 row_ror:2 row_mask:0xf bank_mask:0xf bound_ctrl:1
	ds_write2st64_b32 v41, v36, v66 offset0:30 offset1:31
	s_add_i32 s14, s14, 1
	s_cmpk_eq_i32 s14, 0x100
	s_waitcnt lgkmcnt(0)
	s_barrier
	s_cbranch_scc0 .LBB0_1090
	s_setprio 0
	s_mov_b64 s[44:45], 0
; __device__ __forceinline__ void scan_issue(ScanRegs& R, const bf16_t* PRKV, const unsigned short* WLOG, const bf16_t* ASIG, size_t tok, int ch, int want_prev) {
;     const bf16_t* pp = PRKV + tok * 3072 + ch;
;     R.pr = *(const u32x2*)pp; R.pk = *(const u32x2*)(pp + 1024); R.pv = *(const u32x2*)(pp + 2048);
;     R.qr = (u32x2){0u, 0u}; R.qk = (u32x2){0u, 0u}; R.qv = (u32x2){0u, 0u};
;     if (want_prev == 1) { R.qr = *(const u32x2*)(pp - 3072); R.qk = *(const u32x2*)(pp - 3072 + 1024); R.qv = *(const u32x2*)(pp - 3072 + 2048); }
;     R.wl = *(const u32x2*)(WLOG + tok * 1024 + ch); R.as = *(const u32x2*)(ASIG + tok * 1024 + ch);
; }
; __device__ __forceinline__ void p8_scan(const Args& a, LAS unsigned char* lds) {
;     ...
;     const int p = tid & 255, ltt = p >> 4, cq = p & 15;
;     const int jq4 = 4 * (lane & 15);
;     for (int item = blockIdx.x; item < 256; item += gridDim.x) {
;         const int bh = item & 63, rq = item >> 6, b = bh >> 4, h = bh & 15;
;         const int ch = h * 64 + 4 * cq;
;         const int myrow = 16 * rq + 4 * (w & 3) + (lane >> 4);
;         __syncthreads();
;         if (w >= 4) {
;             const f32x4 mur = *(const f32x4*)(mu_rkv + ch), muk = *(const f32x4*)(mu_rkv + 1024 + ch), muv = *(const f32x4*)(mu_rkv + 2048 + ch),
;                         kkc = *(const f32x4*)(k_k + ch), kac = *(const f32x4*)(k_a + ch), rkc = *(const f32x4*)(r_k + ch);
;             ScanRegs A0, A1, B0, B1;
;             { const size_t tok = (size_t)b * T + 2 * ltt; scan_issue(A0, PRKV, WLOG, ASIG, tok, ch, ltt > 0 ? 1 : 2); scan_issue(A1, PRKV, WLOG, ASIG, tok + 1, ch, 0);
;               const float b0 = scan_prepare(A0, A0.qr, A0.qk, A0.qv, buf + (2 * ltt) * SPITCH, cq, mur, muk, muv, kkc, kac, rkc);
;               const float b1 = scan_prepare(A1, A0.pr, A0.pk, A0.pv, buf + (2 * ltt + 1) * SPITCH, cq, mur, muk, muv, kkc, kac, rkc);
;               if (rq == 0 && cq == 0) { BONUS[tok * 16 + h] = b0; BONUS[(tok + 1) * 16 + h] = b1; }
;               scan_issue(A0, PRKV, WLOG, ASIG, tok + TC, ch, 1); scan_issue(A1, PRKV, WLOG, ASIG, tok + TC + 1, ch, 0);
;               scan_issue(B0, PRKV, WLOG, ASIG, tok + 2 * TC, ch, 1); scan_issue(B1, PRKV, WLOG, ASIG, tok + 2 * TC + 1, ch, 0); }
.LBB0_1094:
	s_and_b64 vcc, exec, s[44:45]
	s_cbranch_vccz .LBB0_1087
	v_mbcnt_lo_u32_b32 v233, -1, 0
	v_mbcnt_hi_u32_b32 v233, -1, v233
	v_and_b32_e32 v235, 16, v233
	v_cmp_ne_u32_e32 vcc, 0, v235
	v_cndmask_b32_e64 v235, 0, 1.0, vcc
	v_cmp_lt_u32_e32 vcc, 31, v233
	v_cndmask_b32_e64 v237, 0, 1.0, vcc
	v_sub_f32_e32 v236, 1.0, v235
	v_sub_f32_e32 v238, 1.0, v237
	v_add_u32_e32 v234, 32, v233
	v_add_u32_e32 v233, 48, v233
	v_and_b32_e32 v234, 63, v234
	v_and_b32_e32 v233, 63, v233
	v_lshlrev_b32_e32 v234, 2, v234
	v_lshlrev_b32_e32 v233, 2, v233
	s_and_b32 s14, s71, 15
	s_lshl_b32 s43, s71, 9
	s_lshl_b32 s88, s14, 6
	s_and_b32 s43, s43, 0x6000
	v_or_b32_e32 v1, s88, v27
	v_or_b32_e32 v139, s43, v125
	v_mov_b64_e32 v[32:33], s[0:1]
	s_movk_i32 s43, 0x1800
	s_waitcnt vmcnt(15)
	v_mad_u64_u32 v[34:35], s[44:45], v139, s43, v[32:33]
	v_lshlrev_b32_e32 v28, 1, v1
	s_mov_b64 s[56:57], s[84:85]
	v_readlane_b32 s72, v232, 16
	v_lshl_add_u64 v[32:33], v[34:35], 0, v[28:29]
	v_lshlrev_b32_e32 v22, 2, v1
	v_readlane_b32 s78, v232, 22
	v_readlane_b32 s79, v232, 23
	s_waitcnt vmcnt(12)
	v_add_co_u32_e32 v36, vcc, 0x1000, v32
	global_load_dwordx4 v[2:5], v22, s[20:21]
	global_load_dwordx4 v[6:9], v22, s[22:23]
	global_load_dwordx4 v[10:13], v22, s[54:55]
	v_readlane_b32 s80, v232, 24
	v_readlane_b32 s81, v232, 25
	v_readlane_b32 s82, v232, 26
	v_readlane_b32 s83, v232, 27
	global_load_dwordx4 v[14:17], v22, s[78:79]
	s_nop 1
	global_load_dwordx4 v[18:21], v22, s[80:81]
	s_nop 0
	global_load_dwordx4 v[22:25], v22, s[82:83]
	v_addc_co_u32_e32 v37, vcc, 0, v33, vcc
	global_load_dwordx2 v[40:41], v[32:33], off
	global_load_dwordx2 v[38:39], v[32:33], off offset:2048
	global_load_dwordx2 v[52:53], v[36:37], off
	s_waitcnt vmcnt(14)
	v_mov_b32_e32 v48, 0
	v_mov_b32_e32 v49, 0
	v_mov_b32_e32 v50, 0
	v_mov_b32_e32 v51, 0
	v_mov_b32_e32 v54, 0
	v_mov_b32_e32 v55, 0
	v_readlane_b32 s73, v232, 17
	v_readlane_b32 s74, v232, 18
	v_readlane_b32 s75, v232, 19
	v_readlane_b32 s76, v232, 20
	v_readlane_b32 s77, v232, 21
	v_readlane_b32 s84, v232, 28
	v_readlane_b32 s85, v232, 29
	v_readlane_b32 s86, v232, 30
	v_readlane_b32 s87, v232, 31
	s_and_saveexec_b64 s[44:45], s[6:7]
	s_cbranch_execz .LBB0_1097
	v_add_co_u32_e32 v36, vcc, 0xfffff000, v32
	s_nop 1
	v_addc_co_u32_e32 v37, vcc, -1, v33, vcc
	global_load_dwordx2 v[48:49], v[36:37], off offset:-2048
	global_load_dwordx2 v[50:51], v[32:33], off offset:-4096
	global_load_dwordx2 v[54:55], v[32:33], off offset:-2048
.LBB0_1097:
	s_or_b64 exec, exec, s[44:45]
	v_lshlrev_b32_e32 v32, 11, v139
	v_mov_b32_e32 v33, v29
	v_lshl_add_u64 v[42:43], s[90:91], 0, v[32:33]
	v_lshl_add_u64 v[42:43], v[42:43], 0, v[28:29]
	global_load_dwordx2 v[60:61], v[42:43], off
	v_lshl_add_u64 v[36:37], s[8:9], 0, v[32:33]
	v_lshl_add_u64 v[36:37], v[36:37], 0, v[28:29]
	s_mov_b64 s[44:45], 0x1800
	global_load_dwordx2 v[62:63], v[36:37], off
	v_or_b32_e32 v1, 1, v139
	s_waitcnt vmcnt(3)
	v_lshlrev_b32_e32 v46, 16, v38
	v_and_b32_e32 v47, 0xffff0000, v38
	s_waitcnt vmcnt(2)
	v_lshlrev_b32_e32 v36, 16, v52
	v_and_b32_e32 v37, 0xffff0000, v52
	v_lshlrev_b32_e32 v44, 16, v39
	v_and_b32_e32 v45, 0xffff0000, v39
	v_lshlrev_b32_e32 v38, 16, v53
	v_and_b32_e32 v39, 0xffff0000, v53
	v_lshlrev_b32_e32 v52, 16, v55
	v_and_b32_e32 v53, 0xffff0000, v55
	v_lshl_add_u64 v[34:35], v[34:35], 0, s[44:45]
	v_mov_b32_e32 v57, v29
	v_lshlrev_b32_e32 v58, 16, v54
	v_and_b32_e32 v59, 0xffff0000, v54
	v_lshlrev_b32_e32 v54, 16, v50
	v_and_b32_e32 v55, 0xffff0000, v50
	v_lshlrev_b32_e32 v50, 16, v51
	v_and_b32_e32 v51, 0xffff0000, v51
	s_movk_i32 s43, 0x1000
	v_lshlrev_b32_e32 v56, 11, v1
	v_pk_add_f32 v[52:53], v[52:53], v[38:39] neg_lo:[0,1] neg_hi:[0,1]
	v_lshl_add_u64 v[72:73], v[34:35], 0, v[28:29]
	v_lshlrev_b32_e32 v42, 16, v40
	v_and_b32_e32 v43, 0xffff0000, v40
	v_lshlrev_b32_e32 v64, 16, v48
	v_and_b32_e32 v65, 0xffff0000, v48
	v_pk_add_f32 v[70:71], v[50:51], v[44:45] neg_lo:[0,1] neg_hi:[0,1]
	v_lshl_add_u64 v[50:51], s[8:9], 0, v[56:57]
	v_lshl_add_u64 v[56:57], s[90:91], 0, v[56:57]
	v_pk_fma_f32 v[66:67], v[8:9], v[52:53], v[38:39]
	v_add_co_u32_e32 v52, vcc, s43, v72
	v_pk_add_f32 v[58:59], v[58:59], v[36:37] neg_lo:[0,1] neg_hi:[0,1]
	v_pk_add_f32 v[54:55], v[54:55], v[46:47] neg_lo:[0,1] neg_hi:[0,1]
	v_pk_add_f32 v[68:69], v[64:65], v[42:43] neg_lo:[0,1] neg_hi:[0,1]
	v_addc_co_u32_e32 v53, vcc, 0, v73, vcc
	v_lshl_add_u64 v[56:57], v[56:57], 0, v[28:29]
	v_pk_fma_f32 v[64:65], v[6:7], v[58:59], v[36:37]
	v_pk_fma_f32 v[74:75], v[2:3], v[54:55], v[46:47]
	v_pk_fma_f32 v[84:85], v[10:11], v[68:69], v[42:43]
	v_lshl_add_u64 v[68:69], v[50:51], 0, v[28:29]
	global_load_dwordx2 v[50:51], v[72:73], off
	global_load_dwordx2 v[54:55], v[72:73], off offset:2048
	global_load_dwordx2 v[58:59], v[52:53], off
	s_nop 0
	global_load_dwordx2 v[52:53], v[68:69], off
	s_nop 0
	global_load_dwordx2 v[56:57], v[56:57], off
	v_pk_fma_f32 v[70:71], v[4:5], v[70:71], v[44:45]
	v_pk_mul_f32 v[76:77], v[14:15], v[74:75]
	v_pk_mul_f32 v[78:79], v[16:17], v[70:71]
	v_pk_mul_f32 v[68:69], v[76:77], v[76:77]
	v_pk_mul_f32 v[72:73], v[78:79], v[78:79]
	v_add_f32_e32 v33, v68, v69
	v_add_f32_e32 v33, v72, v33
	v_add_f32_e32 v33, v73, v33
	v_lshlrev_b32_e32 v40, 16, v41
	v_and_b32_e32 v41, 0xffff0000, v41
	v_add_f32_dpp v33, v33, v33 row_ror:1 row_mask:0xf bank_mask:0xf bound_ctrl:1
	s_waitcnt vmcnt(6)
; #define LAS __attribute__((address_space(3)))
; __device__ __forceinline__ float f16_to_f(unsigned short h) { return (float)__builtin_bit_cast(_Float16, h); }
; __device__ __forceinline__ float scan_prepare(const ScanRegs& R, const u32x2 qr_, const u32x2 qk_, const u32x2 qv_, LAS float* slot, int cq, const f32x4 mur, const f32x4 muk, const f32x4 muv, const f32x4 kkc, const f32x4 kac, const f32x4 rkc) {
;     float pr[4], pk[4], pv[4], qr[4], qk[4], qv[4], av[4], om[4];
;     unpack4(R.pr, pr); unpack4(R.pk, pk); unpack4(R.pv, pv); unpack4(qr_, qr); unpack4(qk_, qk); unpack4(qv_, qv); unpack4(R.as, av);
;     om[0] = f16_to_f((unsigned short)(R.wl.x & 0xffffu)); om[1] = f16_to_f((unsigned short)(R.wl.x >> 16)); om[2] = f16_to_f((unsigned short)(R.wl.y & 0xffffu)); om[3] = f16_to_f((unsigned short)(R.wl.y >> 16));
;     float rr[4], vv[4], kn[4], k2[4], dec[4], bu[4];
;     float ssq = 0.f, bon = 0.f, c1 = 0.f, c2 = 0.f;
; #pragma unroll
;     for (int j = 0; j < 4; ++j) {
;         rr[j] = pr[j] + (qr[j] - pr[j]) * mur[j]; const float kk0 = pk[j] + (qk[j] - pk[j]) * muk[j]; vv[j] = pv[j] + (qv[j] - pv[j]) * muv[j];
;         dec[j] = 1.0f - om[j];
;         kn[j] = kk0 * kkc[j]; ssq += kn[j] * kn[j];
;         k2[j] = kk0 * (1.0f + (av[j] - 1.0f) * kac[j]);
;         const float t = rr[j] * k2[j]; bon += t * rkc[j]; c2 += t;
;         bu[j] = kn[j] * av[j]; c1 += bu[j] * rr[j];
;     }
;     ssq += dpp_f<0x121>(ssq); bon += dpp_f<0x121>(bon); c1 += dpp_f<0x121>(c1); c2 += dpp_f<0x121>(c2);
;     ssq += dpp_f<0x122>(ssq); bon += dpp_f<0x122>(bon); c1 += dpp_f<0x122>(c1); c2 += dpp_f<0x122>(c2);
;     ssq += dpp_f<0x124>(ssq); bon += dpp_f<0x124>(bon); c1 += dpp_f<0x124>(c1); c2 += dpp_f<0x124>(c2);
;     ssq += dpp_f<0x128>(ssq); bon += dpp_f<0x128>(bon); c1 += dpp_f<0x128>(c1); c2 += dpp_f<0x128>(c2);
;     const float inv = __builtin_amdgcn_rsqf(fmaxf(ssq, 1e-24f));
;     f32x4 o_al, o_be, o_wr;
; #pragma unroll
;     for (int j = 0; j < 4; ++j) { o_al[j] = -(kn[j] * inv); o_be[j] = bu[j] * inv; o_wr[j] = dec[j] * rr[j]; }
;     LAS f32x4* s4 = (LAS f32x4*)slot;
;     s4[cq] = (f32x4){dec[0], dec[1], dec[2], dec[3]}; s4[16 + cq] = (f32x4){k2[0], k2[1], k2[2], k2[3]}; s4[32 + cq] = o_al; s4[48 + cq] = o_be; s4[64 + cq] = o_wr;
;     s4[80 + cq] = (f32x4){vv[0], vv[1], vv[2], vv[3]};
;     if (cq == 0) *(LAS f32x2*)(slot + 384) = (f32x2){c1 * inv, c2};
	v_lshlrev_b32_e32 v68, 16, v60
	v_and_b32_e32 v69, 0xffff0000, v60
	v_pk_add_f32 v[80:81], v[68:69], -1.0 op_sel_hi:[1,0]
	v_add_f32_dpp v33, v33, v33 row_ror:2 row_mask:0xf bank_mask:0xf bound_ctrl:1
	v_pk_mul_f32 v[86:87], v[76:77], v[68:69]
	v_pk_fma_f32 v[68:69], v[18:19], v[80:81], 1.0 op_sel_hi:[1,1,0]
	v_add_f32_dpp v33, v33, v33 row_ror:4 row_mask:0xf bank_mask:0xf bound_ctrl:1
	v_pk_mul_f32 v[68:69], v[74:75], v[68:69]
	s_nop 0
	v_add_f32_dpp v33, v33, v33 row_ror:8 row_mask:0xf bank_mask:0xf bound_ctrl:1
	v_pk_mul_f32 v[74:75], v[84:85], v[68:69]
	v_max_f32_e32 v33, 0x179abe15, v33
	v_lshlrev_b32_e32 v60, 16, v61
	v_and_b32_e32 v61, 0xffff0000, v61
	v_pk_add_f32 v[82:83], v[60:61], -1.0 op_sel_hi:[1,0]
	v_fma_f32 v91, v22, v74, 0
	v_rsq_f32_e32 v48, v33
	v_fmac_f32_e32 v91, v23, v75
	v_pk_fma_f32 v[74:75], v[20:21], v[82:83], 1.0 op_sel_hi:[1,1,0]
	v_pk_mul_f32 v[60:61], v[78:79], v[60:61]
	v_pk_mul_f32 v[70:71], v[70:71], v[74:75]
	v_lshlrev_b32_e32 v74, 16, v49
	v_and_b32_e32 v75, 0xffff0000, v49
	v_pk_add_f32 v[74:75], v[74:75], v[40:41] neg_lo:[0,1] neg_hi:[0,1]
	v_pk_mul_f32 v[80:81], v[86:87], v[48:49] op_sel_hi:[1,0]
	v_pk_fma_f32 v[86:87], v[12:13], v[74:75], v[40:41]
	s_waitcnt vmcnt(5)
	v_cvt_f32_f16_e32 v72, v62
	v_cvt_f32_f16_sdwa v73, v62 dst_sel:DWORD dst_unused:UNUSED_PAD src0_sel:WORD_1
	v_pk_mul_f32 v[82:83], v[60:61], v[48:49] op_sel_hi:[1,0]
	v_cvt_f32_f16_e32 v62, v63
	v_cvt_f32_f16_sdwa v63, v63 dst_sel:DWORD dst_unused:UNUSED_PAD src0_sel:WORD_1
	v_pk_mul_f32 v[88:89], v[86:87], v[70:71]
	v_pk_mul_f32 v[78:79], v[78:79], v[48:49] op_sel_hi:[1,0] neg_lo:[0,1] neg_hi:[0,1]
	v_pk_mul_f32 v[76:77], v[76:77], v[48:49] op_sel_hi:[1,0] neg_lo:[0,1] neg_hi:[0,1]
	v_fmac_f32_e32 v91, v24, v88
	v_fmac_f32_e32 v91, v25, v89
	s_nop 0
	s_nop 0
	v_add_f32_dpp v60, v91, v91 row_ror:1 row_mask:0xf bank_mask:0xf bound_ctrl:1
	v_pk_add_f32 v[74:75], v[62:63], 1.0 op_sel_hi:[1,0] neg_lo:[1,0] neg_hi:[1,0]
	s_nop 0
	v_add_f32_dpp v60, v60, v60 row_ror:2 row_mask:0xf bank_mask:0xf bound_ctrl:1
	s_nop 1
	v_add_f32_dpp v33, v60, v60 row_ror:4 row_mask:0xf bank_mask:0xf bound_ctrl:1
	v_mov_b32_e32 v49, v29
	v_pk_add_f32 v[72:73], v[72:73], 1.0 op_sel_hi:[1,0] neg_lo:[1,0] neg_hi:[1,0]
	s_nop 0
	v_mov_b32_dpp v49, v33 row_ror:8 row_mask:0xf bank_mask:0xf
	v_pk_mul_f32 v[84:85], v[84:85], 1.0 op_sel_hi:[1,0]
	v_pk_mul_f32 v[86:87], v[86:87], 1.0 op_sel_hi:[1,0]
	v_pk_mov_b32 v[174:175], v[72:73], v[72:73] op_sel:[0,1]
	v_pk_mov_b32 v[176:177], v[74:75], v[74:75] op_sel:[0,1]
	v_pk_mov_b32 v[178:179], v[68:69], v[68:69] op_sel:[0,1]
	v_pk_mov_b32 v[180:181], v[70:71], v[70:71] op_sel:[0,1]
	v_pk_mov_b32 v[182:183], v[76:77], v[76:77] op_sel:[0,1]
	v_pk_mov_b32 v[184:185], v[78:79], v[78:79] op_sel:[0,1]
	v_pk_mov_b32 v[186:187], v[80:81], v[80:81] op_sel:[0,1]
	v_pk_mov_b32 v[188:189], v[82:83], v[82:83] op_sel:[0,1]
	v_pk_mov_b32 v[190:191], v[84:85], v[84:85] op_sel:[0,1]
	v_pk_mov_b32 v[192:193], v[86:87], v[86:87] op_sel:[0,1]
	v_mov_b32_e32 v194, v127
	ds_write_b128 v127, v[64:67] offset:1280
	s_and_saveexec_b64 s[44:45], s[4:5]
	s_or_b64 exec, exec, s[44:45]
	s_waitcnt vmcnt(2)
	v_lshlrev_b32_e32 v70, 16, v58
	v_and_b32_e32 v71, 0xffff0000, v58
	v_lshlrev_b32_e32 v72, 16, v59
	v_and_b32_e32 v73, 0xffff0000, v59
	v_lshlrev_b32_e32 v58, 16, v54
	v_and_b32_e32 v59, 0xffff0000, v54
	v_pk_add_f32 v[46:47], v[46:47], v[58:59] neg_lo:[0,1] neg_hi:[0,1]
	s_waitcnt vmcnt(0)
; #define LAS __attribute__((address_space(3)))
; __device__ __forceinline__ float scan_prepare(const ScanRegs& R, const u32x2 qr_, const u32x2 qk_, const u32x2 qv_, LAS float* slot, int cq, const f32x4 mur, const f32x4 muk, const f32x4 muv, const f32x4 kkc, const f32x4 kac, const f32x4 rkc) {
;     float pr[4], pk[4], pv[4], qr[4], qk[4], qv[4], av[4], om[4];
;     unpack4(R.pr, pr); unpack4(R.pk, pk); unpack4(R.pv, pv); unpack4(qr_, qr); unpack4(qk_, qk); unpack4(qv_, qv); unpack4(R.as, av);
;     om[0] = f16_to_f((unsigned short)(R.wl.x & 0xffffu)); om[1] = f16_to_f((unsigned short)(R.wl.x >> 16)); om[2] = f16_to_f((unsigned short)(R.wl.y & 0xffffu)); om[3] = f16_to_f((unsigned short)(R.wl.y >> 16));
;     float rr[4], vv[4], kn[4], k2[4], dec[4], bu[4];
;     float ssq = 0.f, bon = 0.f, c1 = 0.f, c2 = 0.f;
; #pragma unroll
;     for (int j = 0; j < 4; ++j) {
;         rr[j] = pr[j] + (qr[j] - pr[j]) * mur[j]; const float kk0 = pk[j] + (qk[j] - pk[j]) * muk[j]; vv[j] = pv[j] + (qv[j] - pv[j]) * muv[j];
;         dec[j] = 1.0f - om[j];
;         kn[j] = kk0 * kkc[j]; ssq += kn[j] * kn[j];
;         k2[j] = kk0 * (1.0f + (av[j] - 1.0f) * kac[j]);
;         const float t = rr[j] * k2[j]; bon += t * rkc[j]; c2 += t;
;         bu[j] = kn[j] * av[j]; c1 += bu[j] * rr[j];
;     }
;     ssq += dpp_f<0x121>(ssq); bon += dpp_f<0x121>(bon); c1 += dpp_f<0x121>(c1); c2 += dpp_f<0x121>(c2);
;     ssq += dpp_f<0x122>(ssq); bon += dpp_f<0x122>(bon); c1 += dpp_f<0x122>(c1); c2 += dpp_f<0x122>(c2);
;     ssq += dpp_f<0x124>(ssq); bon += dpp_f<0x124>(bon); c1 += dpp_f<0x124>(c1); c2 += dpp_f<0x124>(c2);
;     ssq += dpp_f<0x128>(ssq); bon += dpp_f<0x128>(bon); c1 += dpp_f<0x128>(c1); c2 += dpp_f<0x128>(c2);
;     const float inv = __builtin_amdgcn_rsqf(fmaxf(ssq, 1e-24f));
;     f32x4 o_al, o_be, o_wr;
; #pragma unroll
;     for (int j = 0; j < 4; ++j) { o_al[j] = -(kn[j] * inv); o_be[j] = bu[j] * inv; o_wr[j] = dec[j] * rr[j]; }
;     LAS f32x4* s4 = (LAS f32x4*)slot;
;     s4[cq] = (f32x4){dec[0], dec[1], dec[2], dec[3]}; s4[16 + cq] = (f32x4){k2[0], k2[1], k2[2], k2[3]}; s4[32 + cq] = o_al; s4[48 + cq] = o_be; s4[64 + cq] = o_wr;
;     s4[80 + cq] = (f32x4){vv[0], vv[1], vv[2], vv[3]};
;     if (cq == 0) *(LAS f32x2*)(slot + 384) = (f32x2){c1 * inv, c2};
;     return bon;
; }
	v_lshlrev_b32_e32 v60, 16, v56
	v_pk_fma_f32 v[46:47], v[2:3], v[46:47], v[58:59]
	v_and_b32_e32 v61, 0xffff0000, v56
	v_pk_mul_f32 v[64:65], v[14:15], v[46:47]
	v_pk_add_f32 v[58:59], v[60:61], -1.0 op_sel_hi:[1,0]
	v_pk_mul_f32 v[74:75], v[64:65], v[60:61]
	v_lshlrev_b32_e32 v60, 16, v50
	v_and_b32_e32 v61, 0xffff0000, v50
	v_pk_fma_f32 v[58:59], v[18:19], v[58:59], 1.0 op_sel_hi:[1,1,0]
	v_pk_add_f32 v[42:43], v[42:43], v[60:61] neg_lo:[0,1] neg_hi:[0,1]
	v_pk_mul_f32 v[58:59], v[46:47], v[58:59]
	v_pk_fma_f32 v[76:77], v[10:11], v[42:43], v[60:61]
	v_pk_mul_f32 v[66:67], v[64:65], v[64:65]
	v_pk_mul_f32 v[42:43], v[76:77], v[58:59]
	v_cvt_f32_f16_sdwa v47, v52 dst_sel:DWORD dst_unused:UNUSED_PAD src0_sel:WORD_1
	v_fma_f32 v48, v22, v42, 0
	v_fmac_f32_e32 v48, v23, v43
	v_lshlrev_b32_e32 v42, 16, v55
	v_and_b32_e32 v43, 0xffff0000, v55
	v_pk_add_f32 v[44:45], v[44:45], v[42:43] neg_lo:[0,1] neg_hi:[0,1]
	v_cvt_f32_f16_e32 v46, v52
	v_pk_fma_f32 v[44:45], v[4:5], v[44:45], v[42:43]
	v_add_f32_e32 v50, v66, v67
	v_pk_mul_f32 v[54:55], v[16:17], v[44:45]
	v_pk_add_f32 v[62:63], v[46:47], 1.0 op_sel_hi:[1,0] neg_lo:[1,0] neg_hi:[1,0]
	v_pk_mul_f32 v[42:43], v[54:55], v[54:55]
	v_add_f32_e32 v42, v42, v50
	v_add_f32_e32 v42, v43, v42
	s_nop 0
	s_nop 0
	v_add_f32_dpp v42, v42, v42 row_ror:1 row_mask:0xf bank_mask:0xf bound_ctrl:1
	v_lshlrev_b32_e32 v46, 16, v57
	v_and_b32_e32 v47, 0xffff0000, v57
	v_add_f32_dpp v42, v42, v42 row_ror:2 row_mask:0xf bank_mask:0xf bound_ctrl:1
	v_pk_add_f32 v[56:57], v[46:47], -1.0 op_sel_hi:[1,0]
	v_cvt_f32_f16_e32 v50, v53
	v_add_f32_dpp v42, v42, v42 row_ror:4 row_mask:0xf bank_mask:0xf bound_ctrl:1
	v_pk_fma_f32 v[56:57], v[20:21], v[56:57], 1.0 op_sel_hi:[1,1,0]
	v_pk_add_f32 v[36:37], v[36:37], v[70:71] neg_lo:[0,1] neg_hi:[0,1]
	v_add_f32_dpp v42, v42, v42 row_ror:8 row_mask:0xf bank_mask:0xf bound_ctrl:1
	v_max_f32_e32 v42, 0x179abe15, v42
	v_rsq_f32_e32 v42, v42
	v_pk_mul_f32 v[60:61], v[44:45], v[56:57]
	v_pk_mul_f32 v[44:45], v[54:55], v[46:47]
	v_lshlrev_b32_e32 v46, 16, v51
	v_and_b32_e32 v47, 0xffff0000, v51
	v_pk_add_f32 v[40:41], v[40:41], v[46:47] neg_lo:[0,1] neg_hi:[0,1]
	v_cvt_f32_f16_sdwa v51, v53 dst_sel:DWORD dst_unused:UNUSED_PAD src0_sel:WORD_1
	v_pk_fma_f32 v[52:53], v[12:13], v[40:41], v[46:47]
	v_pk_mul_f32 v[68:69], v[44:45], v[42:43] op_sel_hi:[1,0]
	v_pk_mul_f32 v[40:41], v[52:53], v[60:61]
	v_pk_mul_f32 v[56:57], v[54:55], v[42:43] op_sel_hi:[1,0] neg_lo:[0,1] neg_hi:[0,1]
	v_pk_mul_f32 v[54:55], v[64:65], v[42:43] op_sel_hi:[1,0] neg_lo:[0,1] neg_hi:[0,1]
	v_pk_mul_f32 v[66:67], v[74:75], v[42:43] op_sel_hi:[1,0]
	v_fmac_f32_e32 v48, v24, v40
	v_fmac_f32_e32 v48, v25, v41
	s_nop 0
	s_nop 0
	v_add_f32_dpp v43, v48, v48 row_ror:1 row_mask:0xf bank_mask:0xf bound_ctrl:1
	s_nop 1
	v_add_f32_dpp v43, v43, v43 row_ror:2 row_mask:0xf bank_mask:0xf bound_ctrl:1
	s_nop 1
	v_add_f32_dpp v40, v43, v43 row_ror:4 row_mask:0xf bank_mask:0xf bound_ctrl:1
	v_mov_b32_e32 v41, v29
	v_pk_add_f32 v[38:39], v[38:39], v[72:73] neg_lo:[0,1] neg_hi:[0,1]
	v_pk_add_f32 v[64:65], v[50:51], 1.0 op_sel_hi:[1,0] neg_lo:[1,0] neg_hi:[1,0]
	v_mov_b32_dpp v41, v40 row_ror:8 row_mask:0xf bank_mask:0xf
	v_pk_fma_f32 v[38:39], v[8:9], v[38:39], v[72:73]
	v_pk_fma_f32 v[36:37], v[6:7], v[36:37], v[70:71]
	v_pk_mul_f32 v[50:51], v[76:77], 1.0 op_sel_hi:[1,0]
	v_pk_mul_f32 v[52:53], v[52:53], 1.0 op_sel_hi:[1,0]
	ds_write_b128 v129, v[36:39] offset:1280
	v_pk_mul_f32 v[196:197], v[174:175], v[62:63]
	v_pk_mul_f32 v[198:199], v[176:177], v[64:65]
	v_mov_b32_e32 v200, v196
	v_mov_b32_e32 v201, v197
	v_mov_b32_e32 v202, v198
	v_mov_b32_e32 v203, v199
	v_mov_b32_e32 v208, v196
	v_mov_b32_e32 v209, v197
	v_mov_b32_e32 v210, v198
	v_mov_b32_e32 v211, v199
	v_permlane16_swap_b32 v200, v208
	v_permlane16_swap_b32 v201, v209
	v_permlane16_swap_b32 v202, v210
	v_permlane16_swap_b32 v203, v211
	v_pk_mul_f32 v[204:205], v[200:201], v[208:209]
	v_pk_mul_f32 v[206:207], v[202:203], v[210:211]
	v_mov_b32_e32 v208, v204
	v_mov_b32_e32 v209, v205
	v_mov_b32_e32 v210, v206
	v_mov_b32_e32 v211, v207
	v_permlane32_swap_b32 v204, v208
	v_permlane32_swap_b32 v205, v209
	v_permlane32_swap_b32 v206, v210
	v_permlane32_swap_b32 v207, v211
	v_fma_f32 v200, v200, v235, v236
	v_fma_f32 v201, v201, v235, v236
	v_fma_f32 v202, v202, v235, v236
	v_fma_f32 v203, v203, v235, v236
	v_fma_f32 v208, v204, v237, v238
	v_fma_f32 v209, v205, v237, v238
	v_fma_f32 v210, v206, v237, v238
	v_fma_f32 v211, v207, v237, v238
	v_pk_mul_f32 v[212:213], v[200:201], v[208:209]
	v_pk_mul_f32 v[214:215], v[202:203], v[210:211]
	v_pk_mul_f32 v[216:217], v[212:213], v[174:175]
	v_pk_mul_f32 v[218:219], v[214:215], v[176:177]
	v_pk_mul_f32 v[220:221], v[216:217], v[62:63]
	v_pk_mul_f32 v[222:223], v[218:219], v[64:65]
	v_rcp_f32_e32 v224, v216
	v_rcp_f32_e32 v225, v217
	v_rcp_f32_e32 v226, v218
	v_rcp_f32_e32 v227, v219
	v_rcp_f32_e32 v228, v220
	v_rcp_f32_e32 v229, v221
	v_rcp_f32_e32 v230, v222
	v_rcp_f32_e32 v231, v223
	s_nop 0
	v_pk_mul_f32 v[182:183], v[182:183], v[212:213]
	v_pk_mul_f32 v[184:185], v[184:185], v[214:215]
	v_pk_mul_f32 v[178:179], v[178:179], v[224:225]
	v_pk_mul_f32 v[180:181], v[180:181], v[226:227]
	ds_write_b128 v194, v[178:181] offset:256
	v_pk_mul_f32 v[186:187], v[186:187], v[224:225]
	v_pk_mul_f32 v[188:189], v[188:189], v[226:227]
	ds_write_b128 v194, v[182:185] offset:512
	v_pk_mul_f32 v[190:191], v[190:191], v[216:217]
	v_pk_mul_f32 v[192:193], v[192:193], v[218:219]
	ds_write_b128 v194, v[186:189] offset:768
	v_pk_mul_f32 v[240:241], v[58:59], v[228:229]
	v_pk_mul_f32 v[242:243], v[60:61], v[230:231]
	ds_write_b128 v194, v[190:193] offset:1024
	v_pk_mul_f32 v[244:245], v[54:55], v[216:217]
	v_pk_mul_f32 v[246:247], v[56:57], v[218:219]
	ds_write_b128 v129, v[220:223]
	v_pk_mul_f32 v[196:197], v[66:67], v[228:229]
	v_pk_mul_f32 v[198:199], v[68:69], v[230:231]
	ds_write_b128 v129, v[240:243] offset:256
	v_pk_mul_f32 v[200:201], v[50:51], v[220:221]
	v_pk_mul_f32 v[202:203], v[52:53], v[222:223]
	ds_write_b128 v129, v[244:247] offset:512
	ds_write_b128 v129, v[196:199] offset:768
	ds_write_b128 v129, v[200:203] offset:1024
	s_and_saveexec_b64 s[44:45], s[4:5]
	s_mov_b64 s[84:85], s[56:57]
	s_or_b64 exec, exec, s[44:45]
	s_cmp_lt_u32 s71, 64
	s_cselect_b64 s[44:45], -1, 0
	s_and_b64 s[44:45], s[4:5], s[44:45]
	s_xor_b64 s[52:53], s[44:45], -1
	v_mov_b64_e32 v[100:101], s[14:15]
	s_and_saveexec_b64 s[56:57], s[52:53]
	s_xor_b64 s[52:53], exec, s[56:57]
	v_mov_b64_e32 v[100:101], s[14:15]
	s_andn2_saveexec_b64 s[52:53], s[52:53]
	s_cbranch_execz .LBB0_1105
	v_lshlrev_b32_e32 v38, 6, v139
	v_mov_b32_e32 v39, v29
	v_lshlrev_b32_e32 v36, 6, v1
	v_mov_b32_e32 v37, v29
	s_lshl_b32 s14, s14, 2
	v_lshl_add_u64 v[38:39], s[12:13], 0, v[38:39]
	v_add_f32_e32 v33, v33, v49
	v_lshl_add_u64 v[36:37], s[12:13], 0, v[36:37]
	v_lshl_add_u64 v[38:39], v[38:39], 0, s[14:15]
	v_lshl_add_u64 v[36:37], v[36:37], 0, s[14:15]
	v_add_f32_e32 v1, v40, v41
	global_store_dword v[38:39], v33, off
	global_store_dword v[36:37], v1, off

; #define LAS __attribute__((address_space(3)))
; __device__ __forceinline__ float f16_to_f(unsigned short h) { return (float)__builtin_bit_cast(_Float16, h); }
; __device__ __forceinline__ float scan_prepare(const ScanRegs& R, const u32x2 qr_, const u32x2 qk_, const u32x2 qv_, LAS float* slot, int cq, const f32x4 mur, const f32x4 muk, const f32x4 muv, const f32x4 kkc, const f32x4 kac, const f32x4 rkc) {
;     float pr[4], pk[4], pv[4], qr[4], qk[4], qv[4], av[4], om[4];
;     unpack4(R.pr, pr); unpack4(R.pk, pk); unpack4(R.pv, pv); unpack4(qr_, qr); unpack4(qk_, qk); unpack4(qv_, qv); unpack4(R.as, av);
;     om[0] = f16_to_f((unsigned short)(R.wl.x & 0xffffu)); om[1] = f16_to_f((unsigned short)(R.wl.x >> 16)); om[2] = f16_to_f((unsigned short)(R.wl.y & 0xffffu)); om[3] = f16_to_f((unsigned short)(R.wl.y >> 16));
;     float rr[4], vv[4], kn[4], k2[4], dec[4], bu[4];
;     float ssq = 0.f, bon = 0.f, c1 = 0.f, c2 = 0.f;
; #pragma unroll
;     for (int j = 0; j < 4; ++j) {
;         rr[j] = pr[j] + (qr[j] - pr[j]) * mur[j]; const float kk0 = pk[j] + (qk[j] - pk[j]) * muk[j]; vv[j] = pv[j] + (qv[j] - pv[j]) * muv[j];
;         dec[j] = 1.0f - om[j];
;         kn[j] = kk0 * kkc[j]; ssq += kn[j] * kn[j];
;         k2[j] = kk0 * (1.0f + (av[j] - 1.0f) * kac[j]);
;         const float t = rr[j] * k2[j]; bon += t * rkc[j]; c2 += t;
;         bu[j] = kn[j] * av[j]; c1 += bu[j] * rr[j];
;     }
;     ssq += dpp_f<0x121>(ssq); bon += dpp_f<0x121>(bon); c1 += dpp_f<0x121>(c1); c2 += dpp_f<0x121>(c2);
;     ssq += dpp_f<0x122>(ssq); bon += dpp_f<0x122>(bon); c1 += dpp_f<0x122>(c1); c2 += dpp_f<0x122>(c2);
;     ssq += dpp_f<0x124>(ssq); bon += dpp_f<0x124>(bon); c1 += dpp_f<0x124>(c1); c2 += dpp_f<0x124>(c2);
;     ssq += dpp_f<0x128>(ssq); bon += dpp_f<0x128>(bon); c1 += dpp_f<0x128>(c1); c2 += dpp_f<0x128>(c2);
;     const float inv = __builtin_amdgcn_rsqf(fmaxf(ssq, 1e-24f));
;     f32x4 o_al, o_be, o_wr;
; #pragma unroll
;     for (int j = 0; j < 4; ++j) { o_al[j] = -(kn[j] * inv); o_be[j] = bu[j] * inv; o_wr[j] = dec[j] * rr[j]; }
;     LAS f32x4* s4 = (LAS f32x4*)slot;
;     s4[cq] = (f32x4){dec[0], dec[1], dec[2], dec[3]}; s4[16 + cq] = (f32x4){k2[0], k2[1], k2[2], k2[3]}; s4[32 + cq] = o_al; s4[48 + cq] = o_be; s4[64 + cq] = o_wr;
;     s4[80 + cq] = (f32x4){vv[0], vv[1], vv[2], vv[3]};
;     if (cq == 0) *(LAS f32x2*)(slot + 384) = (f32x2){c1 * inv, c2};
.LBB0_1109:
	s_waitcnt vmcnt(8)
	v_lshlrev_b32_e32 v108, 16, v46
	v_and_b32_e32 v109, 0xffff0000, v46
	v_lshlrev_b32_e32 v110, 16, v38
	v_and_b32_e32 v111, 0xffff0000, v38
	v_pk_add_f32 v[110:111], v[110:111], v[108:109] neg_lo:[0,1] neg_hi:[0,1]
	v_lshlrev_b32_e32 v140, 16, v39
	v_pk_fma_f32 v[144:145], v[6:7], v[110:111], v[108:109]
	v_lshlrev_b32_e32 v110, 16, v47
	v_and_b32_e32 v111, 0xffff0000, v47
	v_and_b32_e32 v141, 0xffff0000, v39
	v_pk_add_f32 v[140:141], v[140:141], v[110:111] neg_lo:[0,1] neg_hi:[0,1]
	v_lshlrev_b32_e32 v118, 16, v40
	v_and_b32_e32 v119, 0xffff0000, v40
	v_pk_fma_f32 v[146:147], v[8:9], v[140:141], v[110:111]
	v_lshlrev_b32_e32 v140, 16, v34
	v_and_b32_e32 v141, 0xffff0000, v34
	s_waitcnt vmcnt(3)
	v_lshlrev_b32_e32 v142, 16, v48
	v_and_b32_e32 v143, 0xffff0000, v48
	v_pk_add_f32 v[140:141], v[140:141], v[118:119] neg_lo:[0,1] neg_hi:[0,1]
	v_pk_add_f32 v[148:149], v[142:143], -1.0 op_sel_hi:[1,0]
	v_pk_fma_f32 v[140:141], v[2:3], v[140:141], v[118:119]
	v_pk_fma_f32 v[148:149], v[18:19], v[148:149], 1.0 op_sel_hi:[1,1,0]
	v_pk_mul_f32 v[154:155], v[14:15], v[140:141]
	v_pk_mul_f32 v[148:149], v[148:149], v[140:141]
	v_cvt_f32_f16_sdwa v141, v44 dst_sel:DWORD dst_unused:UNUSED_PAD src0_sel:WORD_1
	v_cvt_f32_f16_e32 v140, v44
	v_lshlrev_b32_e32 v114, 16, v36
	v_and_b32_e32 v115, 0xffff0000, v36
	v_lshlrev_b32_e32 v156, 16, v42
	v_and_b32_e32 v157, 0xffff0000, v42
	v_pk_add_f32 v[152:153], v[140:141], 1.0 op_sel_hi:[1,0] neg_lo:[1,0] neg_hi:[1,0]
	v_pk_add_f32 v[140:141], v[156:157], v[114:115] neg_lo:[0,1] neg_hi:[0,1]
	v_lshlrev_b32_e32 v116, 16, v41
	v_pk_fma_f32 v[164:165], v[10:11], v[140:141], v[114:115]
	v_and_b32_e32 v117, 0xffff0000, v41
	v_pk_mul_f32 v[140:141], v[164:165], v[148:149]
	v_pk_mul_f32 v[150:151], v[154:155], v[154:155]
	v_fma_f32 v33, v22, v140, 0
	v_fmac_f32_e32 v33, v23, v141
	v_lshlrev_b32_e32 v140, 16, v35
	v_and_b32_e32 v141, 0xffff0000, v35
	v_pk_add_f32 v[140:141], v[140:141], v[116:117] neg_lo:[0,1] neg_hi:[0,1]
	v_add_f32_e32 v28, v150, v151
	v_pk_fma_f32 v[140:141], v[4:5], v[140:141], v[116:117]
	v_pk_mul_f32 v[142:143], v[154:155], v[142:143]
	v_pk_mul_f32 v[158:159], v[16:17], v[140:141]
	v_pk_mul_f32 v[160:161], v[158:159], v[158:159]
	v_add_f32_e32 v28, v160, v28
	v_add_f32_e32 v28, v161, v28
	v_lshlrev_b32_e32 v156, 16, v49
	s_nop 0
	v_add_f32_dpp v28, v28, v28 row_ror:1 row_mask:0xf bank_mask:0xf bound_ctrl:1
	v_and_b32_e32 v157, 0xffff0000, v49
	v_lshlrev_b32_e32 v112, 16, v37
	v_add_f32_dpp v28, v28, v28 row_ror:2 row_mask:0xf bank_mask:0xf bound_ctrl:1
	v_and_b32_e32 v113, 0xffff0000, v37
	v_pk_add_f32 v[162:163], v[156:157], -1.0 op_sel_hi:[1,0]
	v_add_f32_dpp v28, v28, v28 row_ror:4 row_mask:0xf bank_mask:0xf bound_ctrl:1
	v_pk_fma_f32 v[150:151], v[20:21], v[162:163], 1.0 op_sel_hi:[1,1,0]
	v_pk_mul_f32 v[164:165], v[164:165], 1.0 op_sel_hi:[1,0]
	v_add_f32_dpp v28, v28, v28 row_ror:8 row_mask:0xf bank_mask:0xf bound_ctrl:1
	v_max_f32_e32 v28, 0x179abe15, v28
	v_rsq_f32_e32 v28, v28
	v_pk_mul_f32 v[150:151], v[150:151], v[140:141]
	v_pk_mul_f32 v[140:141], v[158:159], v[156:157]
	v_pk_mul_f32 v[160:161], v[142:143], v[28:29] op_sel_hi:[1,0]
	v_lshlrev_b32_e32 v142, 16, v43
	v_and_b32_e32 v143, 0xffff0000, v43
	v_pk_add_f32 v[142:143], v[142:143], v[112:113] neg_lo:[0,1] neg_hi:[0,1]
	v_pk_mul_f32 v[162:163], v[140:141], v[28:29] op_sel_hi:[1,0]
	v_pk_fma_f32 v[166:167], v[12:13], v[142:143], v[112:113]
	v_pk_mul_f32 v[156:157], v[154:155], v[28:29] op_sel_hi:[1,0] neg_lo:[0,1] neg_hi:[0,1]
	v_pk_mul_f32 v[142:143], v[166:167], v[150:151]
	v_fmac_f32_e32 v33, v24, v142
	v_cvt_f32_f16_sdwa v155, v45 dst_sel:DWORD dst_unused:UNUSED_PAD src0_sel:WORD_1
	v_cvt_f32_f16_e32 v154, v45
	v_fmac_f32_e32 v33, v25, v143
	s_nop 1
	v_add_f32_dpp v33, v33, v33 row_ror:1 row_mask:0xf bank_mask:0xf bound_ctrl:1
	s_nop 1
	v_add_f32_dpp v33, v33, v33 row_ror:2 row_mask:0xf bank_mask:0xf bound_ctrl:1
	s_nop 1
	v_add_f32_dpp v33, v33, v33 row_ror:4 row_mask:0xf bank_mask:0xf bound_ctrl:1
	v_mov_b32_e32 v81, 0
	v_pk_add_f32 v[154:155], v[154:155], 1.0 op_sel_hi:[1,0] neg_lo:[1,0] neg_hi:[1,0]
	s_nop 0
	v_mov_b32_dpp v81, v33 row_ror:8 row_mask:0xf bank_mask:0xf
	v_pk_mul_f32 v[158:159], v[158:159], v[28:29] op_sel_hi:[1,0] neg_lo:[0,1] neg_hi:[0,1]
	v_pk_mul_f32 v[166:167], v[166:167], 1.0 op_sel_hi:[1,0]
	v_pk_mov_b32 v[174:175], v[152:153], v[152:153] op_sel:[0,1]
	v_pk_mov_b32 v[176:177], v[154:155], v[154:155] op_sel:[0,1]
	v_pk_mov_b32 v[178:179], v[148:149], v[148:149] op_sel:[0,1]
	v_pk_mov_b32 v[180:181], v[150:151], v[150:151] op_sel:[0,1]
	v_pk_mov_b32 v[182:183], v[156:157], v[156:157] op_sel:[0,1]
	v_pk_mov_b32 v[184:185], v[158:159], v[158:159] op_sel:[0,1]
	v_pk_mov_b32 v[186:187], v[160:161], v[160:161] op_sel:[0,1]
	v_pk_mov_b32 v[188:189], v[162:163], v[162:163] op_sel:[0,1]
	v_pk_mov_b32 v[190:191], v[164:165], v[164:165] op_sel:[0,1]
	v_pk_mov_b32 v[192:193], v[166:167], v[166:167] op_sel:[0,1]
	v_mov_b32_e32 v194, v127
	ds_write_b128 v127, v[144:147] offset:51456
	s_and_saveexec_b64 s[52:53], s[4:5]
	s_or_b64 exec, exec, s[52:53]
	s_waitcnt vmcnt(17)
	v_lshlrev_b32_e32 v140, 16, v50
	v_and_b32_e32 v141, 0xffff0000, v50
	s_waitcnt vmcnt(2)
	v_lshlrev_b32_e32 v142, 16, v58
	v_and_b32_e32 v143, 0xffff0000, v58
	v_pk_add_f32 v[118:119], v[118:119], v[140:141] neg_lo:[0,1] neg_hi:[0,1]
	v_lshlrev_b32_e32 v150, 16, v59
	v_pk_fma_f32 v[118:119], v[2:3], v[118:119], v[140:141]
	v_pk_add_f32 v[140:141], v[142:143], -1.0 op_sel_hi:[1,0]
	v_pk_mul_f32 v[146:147], v[14:15], v[118:119]
	v_pk_fma_f32 v[140:141], v[18:19], v[140:141], 1.0 op_sel_hi:[1,1,0]
	v_pk_mul_f32 v[152:153], v[146:147], v[142:143]
	v_pk_mul_f32 v[140:141], v[140:141], v[118:119]
	v_cvt_f32_f16_sdwa v119, v52 dst_sel:DWORD dst_unused:UNUSED_PAD src0_sel:WORD_1
	v_cvt_f32_f16_e32 v118, v52
	s_waitcnt vmcnt(6)
; #define LAS __attribute__((address_space(3)))
; __device__ __forceinline__ float scan_prepare(const ScanRegs& R, const u32x2 qr_, const u32x2 qk_, const u32x2 qv_, LAS float* slot, int cq, const f32x4 mur, const f32x4 muk, const f32x4 muv, const f32x4 kkc, const f32x4 kac, const f32x4 rkc) {
;     float pr[4], pk[4], pv[4], qr[4], qk[4], qv[4], av[4], om[4];
;     unpack4(R.pr, pr); unpack4(R.pk, pk); unpack4(R.pv, pv); unpack4(qr_, qr); unpack4(qk_, qk); unpack4(qv_, qv); unpack4(R.as, av);
;     om[0] = f16_to_f((unsigned short)(R.wl.x & 0xffffu)); om[1] = f16_to_f((unsigned short)(R.wl.x >> 16)); om[2] = f16_to_f((unsigned short)(R.wl.y & 0xffffu)); om[3] = f16_to_f((unsigned short)(R.wl.y >> 16));
;     float rr[4], vv[4], kn[4], k2[4], dec[4], bu[4];
;     float ssq = 0.f, bon = 0.f, c1 = 0.f, c2 = 0.f;
; #pragma unroll
;     for (int j = 0; j < 4; ++j) {
;         rr[j] = pr[j] + (qr[j] - pr[j]) * mur[j]; const float kk0 = pk[j] + (qk[j] - pk[j]) * muk[j]; vv[j] = pv[j] + (qv[j] - pv[j]) * muv[j];
;         dec[j] = 1.0f - om[j];
;         kn[j] = kk0 * kkc[j]; ssq += kn[j] * kn[j];
;         k2[j] = kk0 * (1.0f + (av[j] - 1.0f) * kac[j]);
;         const float t = rr[j] * k2[j]; bon += t * rkc[j]; c2 += t;
;         bu[j] = kn[j] * av[j]; c1 += bu[j] * rr[j];
;     }
;     ssq += dpp_f<0x121>(ssq); bon += dpp_f<0x121>(bon); c1 += dpp_f<0x121>(c1); c2 += dpp_f<0x121>(c2);
;     ssq += dpp_f<0x122>(ssq); bon += dpp_f<0x122>(bon); c1 += dpp_f<0x122>(c1); c2 += dpp_f<0x122>(c2);
;     ssq += dpp_f<0x124>(ssq); bon += dpp_f<0x124>(bon); c1 += dpp_f<0x124>(c1); c2 += dpp_f<0x124>(c2);
;     ssq += dpp_f<0x128>(ssq); bon += dpp_f<0x128>(bon); c1 += dpp_f<0x128>(c1); c2 += dpp_f<0x128>(c2);
;     const float inv = __builtin_amdgcn_rsqf(fmaxf(ssq, 1e-24f));
;     f32x4 o_al, o_be, o_wr;
; #pragma unroll
;     for (int j = 0; j < 4; ++j) { o_al[j] = -(kn[j] * inv); o_be[j] = bu[j] * inv; o_wr[j] = dec[j] * rr[j]; }
;     LAS f32x4* s4 = (LAS f32x4*)slot;
;     s4[cq] = (f32x4){dec[0], dec[1], dec[2], dec[3]}; s4[16 + cq] = (f32x4){k2[0], k2[1], k2[2], k2[3]}; s4[32 + cq] = o_al; s4[48 + cq] = o_be; s4[64 + cq] = o_wr;
;     s4[80 + cq] = (f32x4){vv[0], vv[1], vv[2], vv[3]};
;     if (cq == 0) *(LAS f32x2*)(slot + 384) = (f32x2){c1 * inv, c2};
;     return bon;
; }
	v_lshlrev_b32_e32 v142, 16, v82
	v_and_b32_e32 v143, 0xffff0000, v82
	v_pk_add_f32 v[114:115], v[114:115], v[142:143] neg_lo:[0,1] neg_hi:[0,1]
	v_pk_add_f32 v[144:145], v[118:119], 1.0 op_sel_hi:[1,0] neg_lo:[1,0] neg_hi:[1,0]
	v_pk_fma_f32 v[118:119], v[10:11], v[114:115], v[142:143]
	v_pk_mul_f32 v[148:149], v[146:147], v[146:147]
	v_pk_mul_f32 v[114:115], v[118:119], v[140:141]
	v_fma_f32 v156, v22, v114, 0
	v_fmac_f32_e32 v156, v23, v115
	v_lshlrev_b32_e32 v114, 16, v51
	v_and_b32_e32 v115, 0xffff0000, v51
	v_pk_add_f32 v[116:117], v[116:117], v[114:115] neg_lo:[0,1] neg_hi:[0,1]
	v_add_f32_e32 v28, v148, v149
	v_pk_fma_f32 v[114:115], v[4:5], v[116:117], v[114:115]
	v_and_b32_e32 v151, 0xffff0000, v59
	v_pk_mul_f32 v[116:117], v[16:17], v[114:115]
	v_pk_add_f32 v[154:155], v[150:151], -1.0 op_sel_hi:[1,0]
	v_pk_mul_f32 v[142:143], v[116:117], v[116:117]
	s_waitcnt vmcnt(5)
	v_lshlrev_b32_e32 v160, 16, v88
	v_add_f32_e32 v28, v142, v28
	v_add_f32_e32 v28, v143, v28
	v_pk_fma_f32 v[142:143], v[20:21], v[154:155], 1.0 op_sel_hi:[1,1,0]
	v_and_b32_e32 v161, 0xffff0000, v88
	v_add_f32_dpp v28, v28, v28 row_ror:1 row_mask:0xf bank_mask:0xf bound_ctrl:1
	v_pk_mul_f32 v[142:143], v[142:143], v[114:115]
	v_pk_mul_f32 v[114:115], v[116:117], v[150:151]
	v_add_f32_dpp v28, v28, v28 row_ror:2 row_mask:0xf bank_mask:0xf bound_ctrl:1
	v_lshlrev_b32_e32 v162, 16, v89
	v_and_b32_e32 v163, 0xffff0000, v89
	v_add_f32_dpp v28, v28, v28 row_ror:4 row_mask:0xf bank_mask:0xf bound_ctrl:1
	v_pk_add_f32 v[108:109], v[108:109], v[160:161] neg_lo:[0,1] neg_hi:[0,1]
	v_pk_add_f32 v[110:111], v[110:111], v[162:163] neg_lo:[0,1] neg_hi:[0,1]
	v_add_f32_dpp v28, v28, v28 row_ror:8 row_mask:0xf bank_mask:0xf bound_ctrl:1
	v_max_f32_e32 v28, 0x179abe15, v28
	v_rsq_f32_e32 v28, v28
	v_pk_fma_f32 v[110:111], v[8:9], v[110:111], v[162:163]
	v_pk_fma_f32 v[108:109], v[6:7], v[108:109], v[160:161]
	v_pk_mul_f32 v[150:151], v[116:117], v[28:29] op_sel_hi:[1,0] neg_lo:[0,1] neg_hi:[0,1]
	v_lshlrev_b32_e32 v116, 16, v83
	v_and_b32_e32 v117, 0xffff0000, v83
	v_pk_add_f32 v[112:113], v[112:113], v[116:117] neg_lo:[0,1] neg_hi:[0,1]
	v_pk_mul_f32 v[154:155], v[114:115], v[28:29] op_sel_hi:[1,0]
	v_pk_fma_f32 v[158:159], v[12:13], v[112:113], v[116:117]
	v_pk_mul_f32 v[148:149], v[146:147], v[28:29] op_sel_hi:[1,0] neg_lo:[0,1] neg_hi:[0,1]
	v_pk_mul_f32 v[112:113], v[158:159], v[142:143]
	v_fmac_f32_e32 v156, v24, v112
	v_cvt_f32_f16_sdwa v147, v53 dst_sel:DWORD dst_unused:UNUSED_PAD src0_sel:WORD_1
	v_cvt_f32_f16_e32 v146, v53
	v_fmac_f32_e32 v156, v25, v113
	s_nop 1
	v_add_f32_dpp v114, v156, v156 row_ror:1 row_mask:0xf bank_mask:0xf bound_ctrl:1
	s_nop 1
	v_add_f32_dpp v114, v114, v114 row_ror:2 row_mask:0xf bank_mask:0xf bound_ctrl:1
	s_nop 1
	v_add_f32_dpp v112, v114, v114 row_ror:4 row_mask:0xf bank_mask:0xf bound_ctrl:1
	v_mov_b32_e32 v113, 0
	v_pk_add_f32 v[146:147], v[146:147], 1.0 op_sel_hi:[1,0] neg_lo:[1,0] neg_hi:[1,0]
	s_nop 0
	v_mov_b32_dpp v113, v112 row_ror:8 row_mask:0xf bank_mask:0xf
	v_pk_mul_f32 v[152:153], v[152:153], v[28:29] op_sel_hi:[1,0]
	v_pk_mul_f32 v[156:157], v[118:119], 1.0 op_sel_hi:[1,0]
	v_pk_mul_f32 v[158:159], v[158:159], 1.0 op_sel_hi:[1,0]
	ds_write_b128 v129, v[108:111] offset:51456
	v_pk_mul_f32 v[196:197], v[174:175], v[144:145]
	v_pk_mul_f32 v[198:199], v[176:177], v[146:147]
	v_mov_b32_e32 v200, v196
	v_mov_b32_e32 v201, v197
	v_mov_b32_e32 v202, v198
	v_mov_b32_e32 v203, v199
	v_mov_b32_e32 v208, v196
	v_mov_b32_e32 v209, v197
	v_mov_b32_e32 v210, v198
	v_mov_b32_e32 v211, v199
	v_permlane16_swap_b32 v200, v208
	v_permlane16_swap_b32 v201, v209
	v_permlane16_swap_b32 v202, v210
	v_permlane16_swap_b32 v203, v211
	v_pk_mul_f32 v[204:205], v[200:201], v[208:209]
	v_pk_mul_f32 v[206:207], v[202:203], v[210:211]
	v_mov_b32_e32 v208, v204
	v_mov_b32_e32 v209, v205
	v_mov_b32_e32 v210, v206
	v_mov_b32_e32 v211, v207
	v_permlane32_swap_b32 v204, v208
	v_permlane32_swap_b32 v205, v209
	v_permlane32_swap_b32 v206, v210
	v_permlane32_swap_b32 v207, v211
	v_fma_f32 v200, v200, v235, v236
	v_fma_f32 v201, v201, v235, v236
	v_fma_f32 v202, v202, v235, v236
	v_fma_f32 v203, v203, v235, v236
	v_fma_f32 v208, v204, v237, v238
	v_fma_f32 v209, v205, v237, v238
	v_fma_f32 v210, v206, v237, v238
	v_fma_f32 v211, v207, v237, v238
	v_pk_mul_f32 v[212:213], v[200:201], v[208:209]
	v_pk_mul_f32 v[214:215], v[202:203], v[210:211]
	v_pk_mul_f32 v[216:217], v[212:213], v[174:175]
	v_pk_mul_f32 v[218:219], v[214:215], v[176:177]
	v_pk_mul_f32 v[220:221], v[216:217], v[144:145]
	v_pk_mul_f32 v[222:223], v[218:219], v[146:147]
	v_rcp_f32_e32 v224, v216
	v_rcp_f32_e32 v225, v217
	v_rcp_f32_e32 v226, v218
	v_rcp_f32_e32 v227, v219
	v_rcp_f32_e32 v228, v220
	v_rcp_f32_e32 v229, v221
	v_rcp_f32_e32 v230, v222
	v_rcp_f32_e32 v231, v223
	s_nop 0
	v_pk_mul_f32 v[182:183], v[182:183], v[212:213]
	v_pk_mul_f32 v[184:185], v[184:185], v[214:215]
	v_pk_mul_f32 v[178:179], v[178:179], v[224:225]
	v_pk_mul_f32 v[180:181], v[180:181], v[226:227]
	ds_write_b128 v194, v[178:181] offset:50432
	v_pk_mul_f32 v[186:187], v[186:187], v[224:225]
	v_pk_mul_f32 v[188:189], v[188:189], v[226:227]
	ds_write_b128 v194, v[182:185] offset:50688
	v_pk_mul_f32 v[190:191], v[190:191], v[216:217]
	v_pk_mul_f32 v[192:193], v[192:193], v[218:219]
	ds_write_b128 v194, v[186:189] offset:50944
	v_pk_mul_f32 v[240:241], v[140:141], v[228:229]
	v_pk_mul_f32 v[242:243], v[142:143], v[230:231]
	ds_write_b128 v194, v[190:193] offset:51200
	v_pk_mul_f32 v[244:245], v[148:149], v[216:217]
	v_pk_mul_f32 v[246:247], v[150:151], v[218:219]
	ds_write_b128 v129, v[220:223] offset:50176
	v_pk_mul_f32 v[196:197], v[152:153], v[228:229]
	v_pk_mul_f32 v[198:199], v[154:155], v[230:231]
	ds_write_b128 v129, v[240:243] offset:50432
	v_pk_mul_f32 v[200:201], v[156:157], v[220:221]
	v_pk_mul_f32 v[202:203], v[158:159], v[222:223]
	ds_write_b128 v129, v[244:247] offset:50688
	ds_write_b128 v129, v[196:199] offset:50944
	ds_write_b128 v129, v[200:203] offset:51200
	s_and_saveexec_b64 s[52:53], s[4:5]
	s_cbranch_execz .LBB0_1121
	s_or_b64 exec, exec, s[52:53]
	s_and_saveexec_b64 s[52:53], s[44:45]
	s_cbranch_execnz .LBB0_1122

; #define LAS __attribute__((address_space(3)))
; __device__ __forceinline__ float ysum4(const LAS float* p) { const f32x4 a = *(const LAS f32x4*)p; return (a[0] + a[1]) + (a[2] + a[3]); }
.LBB0_1115:
	v_add_u32_e32 v28, v120, v130
	s_waitcnt lgkmcnt(0)
	s_barrier
	ds_read_b128 v[108:111], v28
	v_lshl_add_u64 v[112:113], s[92:93], 0, v[100:101]
	v_add_co_u32_e32 v112, vcc, s68, v112
	s_cmpk_gt_u32 s14, 0xfd
	s_waitcnt lgkmcnt(0)
	v_add_f32_e32 v28, v108, v109
	v_add_f32_e32 v33, v110, v111
	v_add_f32_e32 v28, v28, v33
	v_bfe_u32 v33, v28, 16, 1
	v_add3_u32 v28, v28, v33, s67
	v_addc_co_u32_e32 v113, vcc, 0, v113, vcc
	global_store_short_d16_hi v[112:113], v28, off
	v_add_u32_e32 v28, v120, v131
	ds_read_b128 v[108:111], v28
	s_cselect_b64 s[52:53], -1, 0
	s_and_b64 vcc, exec, s[52:53]
	s_waitcnt lgkmcnt(0)
	v_add_f32_e32 v28, v108, v109
	v_add_f32_e32 v33, v110, v111
	v_add_f32_e32 v28, v28, v33
	v_bfe_u32 v33, v28, 16, 1
	v_add3_u32 v28, v28, v33, s67
	global_store_short_d16_hi v[112:113], v28, off offset:2048
	s_cbranch_vccnz .LBB0_1106
	v_lshlrev_b32_e32 v108, 16, v76
	v_and_b32_e32 v109, 0xffff0000, v76
	v_lshlrev_b32_e32 v110, 16, v62
	v_and_b32_e32 v111, 0xffff0000, v62
	v_pk_add_f32 v[110:111], v[110:111], v[108:109] neg_lo:[0,1] neg_hi:[0,1]
	v_lshlrev_b32_e32 v140, 16, v63
	v_pk_fma_f32 v[144:145], v[6:7], v[110:111], v[108:109]
	v_lshlrev_b32_e32 v110, 16, v77
	v_and_b32_e32 v111, 0xffff0000, v77
	v_and_b32_e32 v141, 0xffff0000, v63
	v_pk_add_f32 v[140:141], v[140:141], v[110:111] neg_lo:[0,1] neg_hi:[0,1]
	v_lshlrev_b32_e32 v118, 16, v64
	v_and_b32_e32 v119, 0xffff0000, v64
	v_pk_fma_f32 v[146:147], v[8:9], v[140:141], v[110:111]
	v_lshlrev_b32_e32 v140, 16, v54
	v_and_b32_e32 v141, 0xffff0000, v54
	s_waitcnt vmcnt(3)
	v_lshlrev_b32_e32 v142, 16, v86
	v_and_b32_e32 v143, 0xffff0000, v86
	v_pk_add_f32 v[140:141], v[140:141], v[118:119] neg_lo:[0,1] neg_hi:[0,1]
	v_pk_add_f32 v[148:149], v[142:143], -1.0 op_sel_hi:[1,0]
	v_pk_fma_f32 v[140:141], v[2:3], v[140:141], v[118:119]
	v_pk_fma_f32 v[148:149], v[18:19], v[148:149], 1.0 op_sel_hi:[1,1,0]
	v_pk_mul_f32 v[154:155], v[14:15], v[140:141]
	v_pk_mul_f32 v[148:149], v[140:141], v[148:149]
	v_cvt_f32_f16_sdwa v141, v72 dst_sel:DWORD dst_unused:UNUSED_PAD src0_sel:WORD_1
	v_cvt_f32_f16_e32 v140, v72
	v_lshlrev_b32_e32 v114, 16, v56
	v_and_b32_e32 v115, 0xffff0000, v56
	v_lshlrev_b32_e32 v156, 16, v68
	v_and_b32_e32 v157, 0xffff0000, v68
	v_pk_add_f32 v[152:153], v[140:141], 1.0 op_sel_hi:[1,0] neg_lo:[1,0] neg_hi:[1,0]
	v_pk_add_f32 v[140:141], v[156:157], v[114:115] neg_lo:[0,1] neg_hi:[0,1]
	v_lshlrev_b32_e32 v116, 16, v65
	v_pk_fma_f32 v[164:165], v[10:11], v[140:141], v[114:115]
	v_and_b32_e32 v117, 0xffff0000, v65
	v_pk_mul_f32 v[140:141], v[164:165], v[148:149]
	v_pk_mul_f32 v[150:151], v[154:155], v[154:155]
	v_fma_f32 v33, v22, v140, 0
	v_fmac_f32_e32 v33, v23, v141
	v_lshlrev_b32_e32 v140, 16, v55
	v_and_b32_e32 v141, 0xffff0000, v55
	v_pk_add_f32 v[140:141], v[140:141], v[116:117] neg_lo:[0,1] neg_hi:[0,1]
	v_add_f32_e32 v28, v150, v151
	v_pk_fma_f32 v[140:141], v[4:5], v[140:141], v[116:117]
	v_pk_mul_f32 v[142:143], v[154:155], v[142:143]
	v_pk_mul_f32 v[158:159], v[16:17], v[140:141]
	v_pk_mul_f32 v[160:161], v[158:159], v[158:159]
	v_add_f32_e32 v28, v160, v28
	v_add_f32_e32 v28, v161, v28
	v_lshlrev_b32_e32 v156, 16, v87
	s_nop 0
	v_add_f32_dpp v28, v28, v28 row_ror:1 row_mask:0xf bank_mask:0xf bound_ctrl:1
	v_and_b32_e32 v157, 0xffff0000, v87
	v_lshlrev_b32_e32 v112, 16, v57
	v_add_f32_dpp v28, v28, v28 row_ror:2 row_mask:0xf bank_mask:0xf bound_ctrl:1
	v_and_b32_e32 v113, 0xffff0000, v57
	v_pk_add_f32 v[162:163], v[156:157], -1.0 op_sel_hi:[1,0]
	v_add_f32_dpp v28, v28, v28 row_ror:4 row_mask:0xf bank_mask:0xf bound_ctrl:1
	v_pk_fma_f32 v[150:151], v[20:21], v[162:163], 1.0 op_sel_hi:[1,1,0]
	v_pk_mul_f32 v[164:165], v[164:165], 1.0 op_sel_hi:[1,0]
	v_add_f32_dpp v28, v28, v28 row_ror:8 row_mask:0xf bank_mask:0xf bound_ctrl:1
	v_max_f32_e32 v28, 0x179abe15, v28
	v_rsq_f32_e32 v28, v28
	v_pk_mul_f32 v[150:151], v[140:141], v[150:151]
	v_pk_mul_f32 v[140:141], v[158:159], v[156:157]
	v_pk_mul_f32 v[160:161], v[142:143], v[28:29] op_sel_hi:[1,0]
	v_lshlrev_b32_e32 v142, 16, v69
	v_and_b32_e32 v143, 0xffff0000, v69
	v_pk_add_f32 v[142:143], v[142:143], v[112:113] neg_lo:[0,1] neg_hi:[0,1]
	v_pk_mul_f32 v[162:163], v[140:141], v[28:29] op_sel_hi:[1,0]
	v_pk_fma_f32 v[166:167], v[12:13], v[142:143], v[112:113]
	v_pk_mul_f32 v[156:157], v[154:155], v[28:29] op_sel_hi:[1,0] neg_lo:[0,1] neg_hi:[0,1]
	v_pk_mul_f32 v[142:143], v[166:167], v[150:151]
	v_fmac_f32_e32 v33, v24, v142
	v_cvt_f32_f16_sdwa v155, v73 dst_sel:DWORD dst_unused:UNUSED_PAD src0_sel:WORD_1
	v_cvt_f32_f16_e32 v154, v73
	v_fmac_f32_e32 v33, v25, v143
	s_nop 1
	v_add_f32_dpp v33, v33, v33 row_ror:1 row_mask:0xf bank_mask:0xf bound_ctrl:1
	s_nop 1
	v_add_f32_dpp v33, v33, v33 row_ror:2 row_mask:0xf bank_mask:0xf bound_ctrl:1
	s_nop 1
	v_add_f32_dpp v33, v33, v33 row_ror:4 row_mask:0xf bank_mask:0xf bound_ctrl:1
	v_mov_b32_e32 v81, 0
	v_pk_add_f32 v[154:155], v[154:155], 1.0 op_sel_hi:[1,0] neg_lo:[1,0] neg_hi:[1,0]
	s_nop 0
	v_mov_b32_dpp v81, v33 row_ror:8 row_mask:0xf bank_mask:0xf
	v_pk_mul_f32 v[158:159], v[158:159], v[28:29] op_sel_hi:[1,0] neg_lo:[0,1] neg_hi:[0,1]
	v_pk_mul_f32 v[166:167], v[166:167], 1.0 op_sel_hi:[1,0]
	v_pk_mov_b32 v[174:175], v[152:153], v[152:153] op_sel:[0,1]
	v_pk_mov_b32 v[176:177], v[154:155], v[154:155] op_sel:[0,1]
	v_pk_mov_b32 v[178:179], v[148:149], v[148:149] op_sel:[0,1]
	v_pk_mov_b32 v[180:181], v[150:151], v[150:151] op_sel:[0,1]
	v_pk_mov_b32 v[182:183], v[156:157], v[156:157] op_sel:[0,1]
	v_pk_mov_b32 v[184:185], v[158:159], v[158:159] op_sel:[0,1]
	v_pk_mov_b32 v[186:187], v[160:161], v[160:161] op_sel:[0,1]
	v_pk_mov_b32 v[188:189], v[162:163], v[162:163] op_sel:[0,1]
	v_pk_mov_b32 v[190:191], v[164:165], v[164:165] op_sel:[0,1]
	v_pk_mov_b32 v[192:193], v[166:167], v[166:167] op_sel:[0,1]
	v_mov_b32_e32 v194, v127
	ds_write_b128 v127, v[144:147] offset:1280
	s_and_saveexec_b64 s[56:57], s[4:5]
	s_or_b64 exec, exec, s[56:57]
	s_waitcnt vmcnt(4)
; #define LAS __attribute__((address_space(3)))
; __device__ __forceinline__ float scan_prepare(const ScanRegs& R, const u32x2 qr_, const u32x2 qk_, const u32x2 qv_, LAS float* slot, int cq, const f32x4 mur, const f32x4 muk, const f32x4 muv, const f32x4 kkc, const f32x4 kac, const f32x4 rkc) {
;     float pr[4], pk[4], pv[4], qr[4], qk[4], qv[4], av[4], om[4];
;     unpack4(R.pr, pr); unpack4(R.pk, pk); unpack4(R.pv, pv); unpack4(qr_, qr); unpack4(qk_, qk); unpack4(qv_, qv); unpack4(R.as, av);
;     om[0] = f16_to_f((unsigned short)(R.wl.x & 0xffffu)); om[1] = f16_to_f((unsigned short)(R.wl.x >> 16)); om[2] = f16_to_f((unsigned short)(R.wl.y & 0xffffu)); om[3] = f16_to_f((unsigned short)(R.wl.y >> 16));
;     float rr[4], vv[4], kn[4], k2[4], dec[4], bu[4];
;     float ssq = 0.f, bon = 0.f, c1 = 0.f, c2 = 0.f;
; #pragma unroll
;     for (int j = 0; j < 4; ++j) {
;         rr[j] = pr[j] + (qr[j] - pr[j]) * mur[j]; const float kk0 = pk[j] + (qk[j] - pk[j]) * muk[j]; vv[j] = pv[j] + (qv[j] - pv[j]) * muv[j];
;         dec[j] = 1.0f - om[j];
;         kn[j] = kk0 * kkc[j]; ssq += kn[j] * kn[j];
;         k2[j] = kk0 * (1.0f + (av[j] - 1.0f) * kac[j]);
;         const float t = rr[j] * k2[j]; bon += t * rkc[j]; c2 += t;
;         bu[j] = kn[j] * av[j]; c1 += bu[j] * rr[j];
;     }
;     ssq += dpp_f<0x121>(ssq); bon += dpp_f<0x121>(bon); c1 += dpp_f<0x121>(c1); c2 += dpp_f<0x121>(c2);
;     ssq += dpp_f<0x122>(ssq); bon += dpp_f<0x122>(bon); c1 += dpp_f<0x122>(c1); c2 += dpp_f<0x122>(c2);
;     ssq += dpp_f<0x124>(ssq); bon += dpp_f<0x124>(bon); c1 += dpp_f<0x124>(c1); c2 += dpp_f<0x124>(c2);
;     ssq += dpp_f<0x128>(ssq); bon += dpp_f<0x128>(bon); c1 += dpp_f<0x128>(c1); c2 += dpp_f<0x128>(c2);
;     const float inv = __builtin_amdgcn_rsqf(fmaxf(ssq, 1e-24f));
;     f32x4 o_al, o_be, o_wr;
; #pragma unroll
;     for (int j = 0; j < 4; ++j) { o_al[j] = -(kn[j] * inv); o_be[j] = bu[j] * inv; o_wr[j] = dec[j] * rr[j]; }
;     LAS f32x4* s4 = (LAS f32x4*)slot;
;     s4[cq] = (f32x4){dec[0], dec[1], dec[2], dec[3]}; s4[16 + cq] = (f32x4){k2[0], k2[1], k2[2], k2[3]}; s4[32 + cq] = o_al; s4[48 + cq] = o_be; s4[64 + cq] = o_wr;
;     s4[80 + cq] = (f32x4){vv[0], vv[1], vv[2], vv[3]};
;     if (cq == 0) *(LAS f32x2*)(slot + 384) = (f32x2){c1 * inv, c2};
;     return bon;
; }
	v_lshlrev_b32_e32 v140, 16, v96
	v_and_b32_e32 v141, 0xffff0000, v96
	s_waitcnt vmcnt(2)
	v_lshlrev_b32_e32 v142, 16, v102
	v_and_b32_e32 v143, 0xffff0000, v102
	v_pk_add_f32 v[118:119], v[118:119], v[140:141] neg_lo:[0,1] neg_hi:[0,1]
	v_lshlrev_b32_e32 v150, 16, v103
	v_pk_fma_f32 v[118:119], v[2:3], v[118:119], v[140:141]
	v_pk_add_f32 v[140:141], v[142:143], -1.0 op_sel_hi:[1,0]
	v_pk_mul_f32 v[146:147], v[14:15], v[118:119]
	v_pk_fma_f32 v[140:141], v[18:19], v[140:141], 1.0 op_sel_hi:[1,1,0]
	v_pk_mul_f32 v[152:153], v[146:147], v[142:143]
	v_pk_mul_f32 v[140:141], v[140:141], v[118:119]
	v_cvt_f32_f16_sdwa v119, v98 dst_sel:DWORD dst_unused:UNUSED_PAD src0_sel:WORD_1
	v_cvt_f32_f16_e32 v118, v98
	v_lshlrev_b32_e32 v142, 16, v84
	v_and_b32_e32 v143, 0xffff0000, v84
	v_pk_add_f32 v[114:115], v[114:115], v[142:143] neg_lo:[0,1] neg_hi:[0,1]
	v_pk_add_f32 v[144:145], v[118:119], 1.0 op_sel_hi:[1,0] neg_lo:[1,0] neg_hi:[1,0]
	v_pk_fma_f32 v[118:119], v[10:11], v[114:115], v[142:143]
	v_pk_mul_f32 v[148:149], v[146:147], v[146:147]
	v_pk_mul_f32 v[114:115], v[118:119], v[140:141]
	v_fma_f32 v156, v22, v114, 0
	v_fmac_f32_e32 v156, v23, v115
	v_lshlrev_b32_e32 v114, 16, v97
	v_and_b32_e32 v115, 0xffff0000, v97
	v_pk_add_f32 v[116:117], v[116:117], v[114:115] neg_lo:[0,1] neg_hi:[0,1]
	v_add_f32_e32 v28, v148, v149
	v_pk_fma_f32 v[114:115], v[4:5], v[116:117], v[114:115]
	v_and_b32_e32 v151, 0xffff0000, v103
	v_pk_mul_f32 v[116:117], v[16:17], v[114:115]
	v_pk_add_f32 v[154:155], v[150:151], -1.0 op_sel_hi:[1,0]
	v_pk_mul_f32 v[142:143], v[116:117], v[116:117]
	v_lshlrev_b32_e32 v160, 16, v94
	v_add_f32_e32 v28, v142, v28
	v_add_f32_e32 v28, v143, v28
	v_pk_fma_f32 v[142:143], v[20:21], v[154:155], 1.0 op_sel_hi:[1,1,0]
	v_and_b32_e32 v161, 0xffff0000, v94
	v_add_f32_dpp v28, v28, v28 row_ror:1 row_mask:0xf bank_mask:0xf bound_ctrl:1
	v_pk_mul_f32 v[142:143], v[142:143], v[114:115]
	v_pk_mul_f32 v[114:115], v[116:117], v[150:151]
	v_add_f32_dpp v28, v28, v28 row_ror:2 row_mask:0xf bank_mask:0xf bound_ctrl:1
	v_lshlrev_b32_e32 v162, 16, v95
	v_and_b32_e32 v163, 0xffff0000, v95
	v_add_f32_dpp v28, v28, v28 row_ror:4 row_mask:0xf bank_mask:0xf bound_ctrl:1
	v_pk_add_f32 v[108:109], v[108:109], v[160:161] neg_lo:[0,1] neg_hi:[0,1]
	v_pk_add_f32 v[110:111], v[110:111], v[162:163] neg_lo:[0,1] neg_hi:[0,1]
	v_add_f32_dpp v28, v28, v28 row_ror:8 row_mask:0xf bank_mask:0xf bound_ctrl:1
	v_max_f32_e32 v28, 0x179abe15, v28
	v_rsq_f32_e32 v28, v28
	v_pk_fma_f32 v[110:111], v[8:9], v[110:111], v[162:163]
	v_pk_fma_f32 v[108:109], v[6:7], v[108:109], v[160:161]
	v_pk_mul_f32 v[150:151], v[116:117], v[28:29] op_sel_hi:[1,0] neg_lo:[0,1] neg_hi:[0,1]
	v_lshlrev_b32_e32 v116, 16, v85
	v_and_b32_e32 v117, 0xffff0000, v85
	v_pk_add_f32 v[112:113], v[112:113], v[116:117] neg_lo:[0,1] neg_hi:[0,1]
	v_pk_mul_f32 v[154:155], v[114:115], v[28:29] op_sel_hi:[1,0]
	v_pk_fma_f32 v[158:159], v[12:13], v[112:113], v[116:117]
	v_pk_mul_f32 v[148:149], v[146:147], v[28:29] op_sel_hi:[1,0] neg_lo:[0,1] neg_hi:[0,1]
	v_pk_mul_f32 v[112:113], v[158:159], v[142:143]
	v_fmac_f32_e32 v156, v24, v112
	v_cvt_f32_f16_sdwa v147, v99 dst_sel:DWORD dst_unused:UNUSED_PAD src0_sel:WORD_1
	v_cvt_f32_f16_e32 v146, v99
	v_fmac_f32_e32 v156, v25, v113
	s_nop 1
	v_add_f32_dpp v114, v156, v156 row_ror:1 row_mask:0xf bank_mask:0xf bound_ctrl:1
	s_nop 1
	v_add_f32_dpp v114, v114, v114 row_ror:2 row_mask:0xf bank_mask:0xf bound_ctrl:1
	s_nop 1
	v_add_f32_dpp v112, v114, v114 row_ror:4 row_mask:0xf bank_mask:0xf bound_ctrl:1
	v_mov_b32_e32 v113, 0
	v_pk_add_f32 v[146:147], v[146:147], 1.0 op_sel_hi:[1,0] neg_lo:[1,0] neg_hi:[1,0]
	s_nop 0
	v_mov_b32_dpp v113, v112 row_ror:8 row_mask:0xf bank_mask:0xf
	v_pk_mul_f32 v[152:153], v[152:153], v[28:29] op_sel_hi:[1,0]
	v_pk_mul_f32 v[156:157], v[118:119], 1.0 op_sel_hi:[1,0]
	v_pk_mul_f32 v[158:159], v[158:159], 1.0 op_sel_hi:[1,0]
	ds_write_b128 v129, v[108:111] offset:1280
	v_pk_mul_f32 v[196:197], v[174:175], v[144:145]
	v_pk_mul_f32 v[198:199], v[176:177], v[146:147]
	v_mov_b32_e32 v200, v196
	v_mov_b32_e32 v201, v197
	v_mov_b32_e32 v202, v198
	v_mov_b32_e32 v203, v199
	v_mov_b32_e32 v208, v196
	v_mov_b32_e32 v209, v197
	v_mov_b32_e32 v210, v198
	v_mov_b32_e32 v211, v199
	v_permlane16_swap_b32 v200, v208
	v_permlane16_swap_b32 v201, v209
	v_permlane16_swap_b32 v202, v210
	v_permlane16_swap_b32 v203, v211
	v_pk_mul_f32 v[204:205], v[200:201], v[208:209]
	v_pk_mul_f32 v[206:207], v[202:203], v[210:211]
	v_mov_b32_e32 v208, v204
	v_mov_b32_e32 v209, v205
	v_mov_b32_e32 v210, v206
	v_mov_b32_e32 v211, v207
	v_permlane32_swap_b32 v204, v208
	v_permlane32_swap_b32 v205, v209
	v_permlane32_swap_b32 v206, v210
	v_permlane32_swap_b32 v207, v211
	v_fma_f32 v200, v200, v235, v236
	v_fma_f32 v201, v201, v235, v236
	v_fma_f32 v202, v202, v235, v236
	v_fma_f32 v203, v203, v235, v236
	v_fma_f32 v208, v204, v237, v238
	v_fma_f32 v209, v205, v237, v238
	v_fma_f32 v210, v206, v237, v238
	v_fma_f32 v211, v207, v237, v238
	v_pk_mul_f32 v[212:213], v[200:201], v[208:209]
	v_pk_mul_f32 v[214:215], v[202:203], v[210:211]
	v_pk_mul_f32 v[216:217], v[212:213], v[174:175]
	v_pk_mul_f32 v[218:219], v[214:215], v[176:177]
	v_pk_mul_f32 v[220:221], v[216:217], v[144:145]
	v_pk_mul_f32 v[222:223], v[218:219], v[146:147]
	v_rcp_f32_e32 v224, v216
	v_rcp_f32_e32 v225, v217
	v_rcp_f32_e32 v226, v218
	v_rcp_f32_e32 v227, v219
	v_rcp_f32_e32 v228, v220
	v_rcp_f32_e32 v229, v221
	v_rcp_f32_e32 v230, v222
	v_rcp_f32_e32 v231, v223
	s_nop 0
	v_pk_mul_f32 v[182:183], v[182:183], v[212:213]
	v_pk_mul_f32 v[184:185], v[184:185], v[214:215]
	v_pk_mul_f32 v[178:179], v[178:179], v[224:225]
	v_pk_mul_f32 v[180:181], v[180:181], v[226:227]
	ds_write_b128 v194, v[178:181] offset:256
	v_pk_mul_f32 v[186:187], v[186:187], v[224:225]
	v_pk_mul_f32 v[188:189], v[188:189], v[226:227]
	ds_write_b128 v194, v[182:185] offset:512
	v_pk_mul_f32 v[190:191], v[190:191], v[216:217]
	v_pk_mul_f32 v[192:193], v[192:193], v[218:219]
	ds_write_b128 v194, v[186:189] offset:768
	v_pk_mul_f32 v[240:241], v[140:141], v[228:229]
	v_pk_mul_f32 v[242:243], v[142:143], v[230:231]
	ds_write_b128 v194, v[190:193] offset:1024
	v_pk_mul_f32 v[244:245], v[148:149], v[216:217]
	v_pk_mul_f32 v[246:247], v[150:151], v[218:219]
	ds_write_b128 v129, v[220:223]
	v_pk_mul_f32 v[196:197], v[152:153], v[228:229]
	v_pk_mul_f32 v[198:199], v[154:155], v[230:231]
	ds_write_b128 v129, v[240:243] offset:256
	v_pk_mul_f32 v[200:201], v[156:157], v[220:221]
	v_pk_mul_f32 v[202:203], v[158:159], v[222:223]
	ds_write_b128 v129, v[244:247] offset:512
	ds_write_b128 v129, v[196:199] offset:768
	ds_write_b128 v129, v[200:203] offset:1024
	s_and_saveexec_b64 s[56:57], s[4:5]
	s_cbranch_execz .LBB0_1123
	s_or_b64 exec, exec, s[56:57]
	s_and_saveexec_b64 s[56:57], s[44:45]
	s_cbranch_execnz .LBB0_1124
